# LRU gate math: max(1-a*a,0) folded into v_fma_f32 clamp (56 fewer VALU per wave per unit, bit-identical)
# speedup vs baseline: 1.0028x; 1.0028x over previous
; #define LAS __attribute__((address_space(3)))
; template <int MODE>
; __device__ __forceinline__ void lru_unit(const Args& a, int l, int b, int ch, LAS unsigned char* lds) {
;     ...
;     const int tid = tid_, w = __builtin_amdgcn_readfirstlane(tid >> 6), lane = tid & 63, r32 = lane & 31, h = lane >> 5;
;     const int c = w * 64 + lane, t0 = ch * 32;
;     const bf16* proj = (const bf16*)(a.ws + WS_PROJ);
;     LAS unsigned char* xcb = lds + w * 12800;
;     LAS float* au = (LAS float*)(lds + w * 12800 + 4608);
;     const float* cw = a.in[7] + (size_t)l * 4 * LW;
;     const float cw0 = cw[c], cw1 = cw[LW + c], cw2 = cw[2 * LW + c], cw3 = cw[3 * LW + c], cb = a.in[8][l * LW + c];
;     float prm[2][2][3];
; #pragma unroll
;     for (int d = 0; d < 2; ++d)
; #pragma unroll
;         for (int nt = 0; nt < 2; ++nt) { const int cc = (l * 2 + d) * LW + w * 64 + nt * 32 + r32;
;             prm[d][nt][0] = a.in[10][cc]; prm[d][nt][1] = a.in[12][cc]; prm[d][nt][2] = a.in[13][cc]; }
;     const bf16* xp = proj + (size_t)b * SEQ * DIN + c;
;     float xin[35], gl[32];
;     unsigned short xraw[35], graw[32];
; #pragma unroll
;     for (int i = 0; i < 35; ++i) { const int t = t0 - 2 + i, tc = t < 0 ? 0 : (t >= SEQ ? SEQ - 1 : t); xraw[i] = xp[(size_t)tc * DIN]; }
.LBB0_180:
	s_cmpk_gt_i32 s65, 0xff
	s_mov_b64 s[0:1], -1
	s_barrier
	s_cbranch_scc0 .LBB0_182
	s_add_i32 s0, s65, 0xffffff00
	s_lshr_b32 s40, s0, 7
	s_mul_i32 s88, s40, 0x700000
	s_and_b32 s28, s65, 0x7f
	s_lshl_b32 s29, s28, 5
	s_lshl_b64 s[0:1], s[88:89], 1
	s_add_u32 s38, s24, s0
	s_addc_u32 s39, s25, s1
	s_lshl_b32 s0, s40, 21
	s_lshl_b32 s1, s28, 14
	s_or_b32 s88, s0, s1
	s_min_u32 s41, s29, 0xfdf
	s_lshl_b64 s[0:1], s[88:89], 2
	s_add_u32 s44, s72, s0
	s_addc_u32 s45, s73, s1
	s_add_u32 s46, s50, s0
	s_addc_u32 s47, s51, s1
	s_lshl_b32 s0, s40, 17
	s_lshl_b32 s1, s28, 10
	s_or_b32 s88, s0, s1
	s_lshl_b64 s[0:1], s[88:89], 3
	s_add_u32 s42, s74, s0
	s_addc_u32 s43, s75, s1
	v_mov_b32_e32 v66, v226
	s_add_u32 s40, s50, s0
	s_movk_i32 s59, 0xffc0
	v_readfirstlane_b32 s0, v66
	s_mul_i32 s88, s28, 0x1c000
	s_mov_b32 s4, 0x1c000
	v_mov_b32_e32 v0, s0
	v_bfi_b32 v82, s59, v0, v66
	v_ashrrev_i32_e32 v83, 31, v82
	v_lshl_add_u64 v[36:37], v[82:83], 1, s[38:39]
	v_lshl_add_u64 v[4:5], v[36:37], 0, s[88:89]
	v_mov_b32_e32 v214, 0x1c00
	v_mov_b32_e32 v215, 0
	v_mov_b32_e32 v212, v4
	v_mov_b32_e32 v213, v5
	global_load_ushort v210, v[212:213], off
	global_load_ushort v210, v[212:213], off offset:3584
	v_lshl_add_u64 v[212:213], v[212:213], 0, v[214:215]
	global_load_ushort v210, v[212:213], off
	global_load_ushort v210, v[212:213], off offset:3584
	v_lshl_add_u64 v[212:213], v[212:213], 0, v[214:215]
	global_load_ushort v210, v[212:213], off
	global_load_ushort v210, v[212:213], off offset:3584
	v_lshl_add_u64 v[212:213], v[212:213], 0, v[214:215]
	global_load_ushort v210, v[212:213], off
	global_load_ushort v210, v[212:213], off offset:3584
	v_lshl_add_u64 v[212:213], v[212:213], 0, v[214:215]
	global_load_ushort v210, v[212:213], off
	global_load_ushort v210, v[212:213], off offset:3584
	v_lshl_add_u64 v[212:213], v[212:213], 0, v[214:215]
	global_load_ushort v210, v[212:213], off
	global_load_ushort v210, v[212:213], off offset:3584
	v_lshl_add_u64 v[212:213], v[212:213], 0, v[214:215]
	global_load_ushort v210, v[212:213], off
	global_load_ushort v210, v[212:213], off offset:3584
	v_lshl_add_u64 v[212:213], v[212:213], 0, v[214:215]
	global_load_ushort v210, v[212:213], off
	global_load_ushort v210, v[212:213], off offset:3584
	v_lshl_add_u64 v[212:213], v[212:213], 0, v[214:215]
	global_load_ushort v210, v[212:213], off
	global_load_ushort v210, v[212:213], off offset:3584
	v_lshl_add_u64 v[212:213], v[212:213], 0, v[214:215]
	global_load_ushort v210, v[212:213], off
	global_load_ushort v210, v[212:213], off offset:3584
	v_lshl_add_u64 v[212:213], v[212:213], 0, v[214:215]
	global_load_ushort v210, v[212:213], off
	global_load_ushort v210, v[212:213], off offset:3584
	v_lshl_add_u64 v[212:213], v[212:213], 0, v[214:215]
	global_load_ushort v210, v[212:213], off
	global_load_ushort v210, v[212:213], off offset:3584
	v_lshl_add_u64 v[212:213], v[212:213], 0, v[214:215]
	global_load_ushort v210, v[212:213], off
	global_load_ushort v210, v[212:213], off offset:3584
	v_lshl_add_u64 v[212:213], v[212:213], 0, v[214:215]
	global_load_ushort v210, v[212:213], off
	global_load_ushort v210, v[212:213], off offset:3584
	v_lshl_add_u64 v[212:213], v[212:213], 0, v[214:215]
	global_load_ushort v210, v[212:213], off
	global_load_ushort v210, v[212:213], off offset:3584
	v_lshl_add_u64 v[212:213], v[212:213], 0, v[214:215]
	global_load_ushort v210, v[212:213], off
	global_load_ushort v210, v[212:213], off offset:3584
	v_lshl_add_u64 v[212:213], v[212:213], 0, v[214:215]
	s_mul_i32 s88, s41, 0xe00
	v_lshl_add_u64 v[2:3], v[36:37], 0, s[88:89]
	v_add_co_u32_e32 v2, vcc, s4, v2
	v_readlane_b32 s4, v254, 37
	s_nop 0
	v_addc_co_u32_e32 v3, vcc, 0, v3, vcc
	global_load_ushort v0, v[2:3], off
	v_lshlrev_b64 v[2:3], 2, v[82:83]
	v_readlane_b32 s5, v254, 38
	s_movk_i32 s61, 0x1000
	s_movk_i32 s59, 0x2000
	v_lshl_add_u64 v[24:25], s[4:5], 0, v[2:3]
	v_add_co_u32_e32 v26, vcc, s61, v24
	s_movk_i32 s60, 0x3000
	s_nop 0
	v_addc_co_u32_e32 v27, vcc, 0, v25, vcc
	v_add_co_u32_e32 v30, vcc, s61, v4
	s_addc_u32 s41, s51, s1
	s_nop 0
	v_addc_co_u32_e32 v31, vcc, 0, v5, vcc
	v_add_co_u32_e32 v28, vcc, s59, v4
	s_movk_i32 s1, 0x4000
	s_nop 0
	v_addc_co_u32_e32 v29, vcc, 0, v5, vcc
	v_add_co_u32_e32 v32, vcc, s60, v4
	v_and_b32_e32 v164, 31, v66
	s_nop 0
	v_addc_co_u32_e32 v33, vcc, 0, v5, vcc
	v_add_co_u32_e32 v22, vcc, s1, v4
	s_movk_i32 s1, 0x5000
	s_nop 0
	v_addc_co_u32_e32 v23, vcc, 0, v5, vcc
	v_add_co_u32_e32 v10, vcc, s1, v4
	s_movk_i32 s1, 0x6000
	s_nop 0
	v_addc_co_u32_e32 v11, vcc, 0, v5, vcc
	v_add_co_u32_e32 v20, vcc, s1, v4
	s_movk_i32 s1, 0x7000
	s_nop 0
	v_addc_co_u32_e32 v21, vcc, 0, v5, vcc
	v_add_co_u32_e32 v18, vcc, s1, v4
	s_mov_b32 s1, 0x8000
	s_nop 0
	v_addc_co_u32_e32 v19, vcc, 0, v5, vcc
	v_add_co_u32_e32 v12, vcc, s1, v4
	s_mov_b32 s1, 0x9000
	s_nop 0
	v_addc_co_u32_e32 v13, vcc, 0, v5, vcc
	v_add_co_u32_e32 v14, vcc, s1, v4
	s_mov_b32 s1, 0xa000
	s_nop 0
	v_addc_co_u32_e32 v15, vcc, 0, v5, vcc
	v_add_co_u32_e32 v16, vcc, s1, v4
	s_mov_b32 s1, 0xc000
	s_nop 0
	v_addc_co_u32_e32 v17, vcc, 0, v5, vcc
	v_add_co_u32_e32 v6, vcc, s90, v4
	v_readlane_b32 s4, v254, 39
	s_nop 0
	v_addc_co_u32_e32 v7, vcc, 0, v5, vcc
	v_add_co_u32_e32 v8, vcc, s1, v4
	s_and_b32 s1, s0, 0xffffffc0
	s_nop 0
	v_addc_co_u32_e32 v9, vcc, 0, v5, vcc
	s_cmpk_lg_i32 s28, 0x7f
	s_cselect_b64 vcc, -1, 0
	s_add_i32 s28, s29, -2
	s_max_i32 s38, s28, 0
	s_add_i32 s29, s29, -1
	s_mul_i32 s88, s38, 0xe00
	s_max_i32 s38, s29, 0
	v_lshl_add_u64 v[34:35], v[36:37], 0, s[88:89]
	s_mul_i32 s88, s38, 0xe00
	v_lshl_add_u64 v[36:37], v[36:37], 0, s[88:89]
	global_load_ushort v64, v[36:37], off
	global_load_ushort v67, v[32:33], off offset:2048
	global_load_ushort v85, v[30:31], off offset:3072
	global_load_ushort v65, v[34:35], off
	v_or_b32_e32 v30, s4, v164
	v_add_u32_e32 v30, s1, v30
	v_ashrrev_i32_e32 v31, 31, v30
	v_readlane_b32 s4, v252, 16
	v_lshlrev_b64 v[32:33], 2, v[30:31]
	v_readlane_b32 s14, v252, 26
	v_readlane_b32 s15, v252, 27
	s_waitcnt vmcnt(4)
; #define LAS __attribute__((address_space(3)))
; __device__ __forceinline__ unsigned f2bf(float f) { unsigned u = __builtin_bit_cast(unsigned, f); return (u + 0x7fffu + ((u >> 16) & 1u)) >> 16; }
; template <int MODE>
; __device__ __forceinline__ void lru_unit(const Args& a, int l, int b, int ch, LAS unsigned char* lds) {
;     ...
;     const float cw0 = cw[c], cw1 = cw[LW + c], cw2 = cw[2 * LW + c], cw3 = cw[3 * LW + c], cb = a.in[8][l * LW + c];
;     float prm[2][2][3];
; #pragma unroll
;     for (int d = 0; d < 2; ++d)
; #pragma unroll
;         for (int nt = 0; nt < 2; ++nt) { const int cc = (l * 2 + d) * LW + w * 64 + nt * 32 + r32;
;             prm[d][nt][0] = a.in[10][cc]; prm[d][nt][1] = a.in[12][cc]; prm[d][nt][2] = a.in[13][cc]; }
;     const bf16* xp = proj + (size_t)b * SEQ * DIN + c;
;     float xin[35], gl[32];
;     unsigned short xraw[35], graw[32];
; #pragma unroll
;     for (int i = 0; i < 35; ++i) { const int t = t0 - 2 + i, tc = t < 0 ? 0 : (t >= SEQ ? SEQ - 1 : t); xraw[i] = xp[(size_t)tc * DIN]; }
;     if (MODE == 1) {
; #pragma unroll
;         for (int t = 0; t < 32; ++t) graw[t] = xp[(size_t)(t0 + t) * DIN + LW];
;     }
;     asm volatile("" ::: "memory");
; #pragma unroll
;     for (int i = 0; i < 35; ++i) { const int t = t0 - 2 + i; xin[i] = (t >= 0 && t < SEQ) ? bf2f(xraw[i]) : 0.f; }
;     if (MODE == 1) {
; #pragma unroll
;         for (int t = 0; t < 32; ++t) gl[t] = gelu_tanh(bf2f(graw[t]));
;     }
;     float xcr[32], hf[32];
; #pragma unroll
;     for (int t = 0; t < 32; ++t) { const float xc = cw0 * xin[t] + cw1 * xin[t + 1] + cw2 * xin[t + 2] + cw3 * xin[t + 3] + cb; xcr[t] = xc; hf[t] = 0.f;
;         *(LAS bf16*)(xcb + t * 144 + lane * 2) = (bf16)f2bf(xc); }
; #pragma unroll
;     for (int d = 0; d < 2; ++d)
; #pragma unroll
;         for (int nt = 0; nt < 2; ++nt) { prm[d][nt][0] *= -1.4426950408889634f; prm[d][nt][1] *= -1.4426950408889634f;
;             prm[d][nt][2] = -8.f * 1.4426950408889634f * log1pf(__expf(-prm[d][nt][2])); }
	v_lshlrev_b32_e32 v0, 16, v0
	s_mov_b32 s1, 0xd000
	v_lshl_add_u64 v[68:69], s[14:15], 0, v[32:33]
	global_load_dword v30, v[68:69], off
	global_load_ushort v87, v[4:5], off offset:3584
	v_cndmask_b32_e32 v31, 0, v0, vcc
	v_add_co_u32_e32 v34, vcc, s1, v4
	s_mov_b32 s1, 0xe000
	s_nop 0
	v_addc_co_u32_e32 v35, vcc, 0, v5, vcc
	v_add_co_u32_e32 v36, vcc, s1, v4
	s_mov_b32 s1, 0xf000
	s_nop 0
	v_addc_co_u32_e32 v37, vcc, 0, v5, vcc
	v_add_co_u32_e32 v38, vcc, s1, v4
	s_mov_b32 s1, 0x11000
	s_nop 0
	v_addc_co_u32_e32 v39, vcc, 0, v5, vcc
	v_add_co_u32_e32 v40, vcc, s70, v4
	global_load_dword v84, v[68:69], off offset:128
	global_load_dword v88, v[68:69], off offset:2048
	global_load_dword v86, v[68:69], off offset:2176
	v_addc_co_u32_e32 v41, vcc, 0, v5, vcc
	v_add_co_u32_e32 v42, vcc, s1, v4
	s_mov_b32 s1, 0x12000
	s_nop 0
	v_addc_co_u32_e32 v43, vcc, 0, v5, vcc
	v_add_co_u32_e32 v44, vcc, s1, v4
	s_mov_b32 s1, 0x13000
	s_nop 0
	v_addc_co_u32_e32 v45, vcc, 0, v5, vcc
	v_add_co_u32_e32 v46, vcc, s1, v4
	s_mov_b32 s1, 0x14000
	s_nop 0
	v_addc_co_u32_e32 v47, vcc, 0, v5, vcc
	v_add_co_u32_e32 v48, vcc, s1, v4
	s_mov_b32 s1, 0x15000
	s_nop 0
	v_addc_co_u32_e32 v49, vcc, 0, v5, vcc
	v_add_co_u32_e32 v50, vcc, s1, v4
	s_mov_b32 s1, 0x17000
	s_nop 0
	v_addc_co_u32_e32 v51, vcc, 0, v5, vcc
	v_add_co_u32_e32 v52, vcc, s71, v4
	v_readlane_b32 s6, v252, 18
	s_nop 0
	v_addc_co_u32_e32 v53, vcc, 0, v5, vcc
	v_add_co_u32_e32 v54, vcc, s1, v4
	s_mov_b32 s1, 0x18000
	s_nop 0
	v_addc_co_u32_e32 v55, vcc, 0, v5, vcc
	v_add_co_u32_e32 v56, vcc, s1, v4
	s_mov_b32 s1, 0x19000
	s_nop 0
	v_addc_co_u32_e32 v57, vcc, 0, v5, vcc
	v_add_co_u32_e32 v58, vcc, s1, v4
	s_mov_b32 s1, 0x1b000
	s_nop 0
	v_addc_co_u32_e32 v59, vcc, 0, v5, vcc
	v_add_co_u32_e32 v60, vcc, s1, v4
	s_mov_b32 s1, 0x1a000
	s_nop 0
	v_addc_co_u32_e32 v61, vcc, 0, v5, vcc
	v_add_co_u32_e32 v62, vcc, s1, v4
	s_ashr_i32 s1, s0, 6
	s_mul_i32 s0, s1, 0x3200
	s_add_i32 s0, s0, 0
	v_addc_co_u32_e32 v63, vcc, 0, v5, vcc
	s_waitcnt vmcnt(4)
	v_mul_f32_e32 v30, 0xbfb8aa3b, v30
	v_exp_f32_e32 v30, v30
	s_cmpk_lt_u32 s28, 0x1000
	s_cselect_b64 vcc, -1, 0
	s_cmpk_lt_u32 s29, 0x1000
	v_lshlrev_b32_e32 v0, 16, v65
	v_lshlrev_b32_e32 v64, 16, v64
	s_cselect_b64 s[38:39], -1, 0
	v_cndmask_b32_e64 v65, 0, v64, s[38:39]
	v_cndmask_b32_e32 v64, 0, v0, vcc
	s_mov_b32 s6, 0x3f2aaaab
	v_readlane_b32 s7, v252, 19
	s_mov_b32 s7, 0x3f317218
	v_readlane_b32 s10, v252, 22
	s_mov_b32 s10, 0x7f800000
	v_readlane_b32 s11, v252, 23
	s_waitcnt vmcnt(2)
	v_mul_f32_e32 v68, 0xbfb8aa3b, v84
	v_exp_f32_e32 v84, v68
	s_mov_b32 s11, 0x33800000
	s_lshl_b32 s28, s1, 1
	s_ashr_i32 s29, s28, 31
	s_lshl_b64 s[28:29], s[28:29], 13
	v_readlane_b32 s1, v254, 40
	s_add_u32 s28, s1, s28
	v_add_f32_e32 v216, 1.0, v30
	v_add_f32_e32 v217, -1.0, v216
	v_log_f32_e32 v218, v216
	v_rcp_f32_e32 v219, v217
	v_cmp_eq_f32_e32 vcc, 0, v217
	v_mul_f32_e32 v218, v218, v30
	v_mul_f32_e32 v218, 0x3f317218, v218
	v_mul_f32_e32 v218, v218, v219
	v_cndmask_b32_e32 v126, v218, v30, vcc
	v_readlane_b32 s1, v254, 41
	v_bfe_u32 v165, v66, 5, 1
	s_addc_u32 s29, s1, s29
	s_waitcnt vmcnt(1)
	v_mul_f32_e32 v30, 0xbfb8aa3b, v88
	v_exp_f32_e32 v163, v30
	v_readlane_b32 s14, v254, 43
	v_readlane_b32 s5, v252, 17
	v_readlane_b32 s8, v252, 20
	v_readlane_b32 s9, v252, 21
	v_readlane_b32 s12, v252, 24
	v_readlane_b32 s13, v252, 25
	v_add_f32_e32 v216, 1.0, v84
	v_add_f32_e32 v217, -1.0, v216
	v_log_f32_e32 v218, v216
	v_rcp_f32_e32 v219, v217
	v_cmp_eq_f32_e32 vcc, 0, v217
	v_mul_f32_e32 v218, v218, v84
	v_mul_f32_e32 v218, 0x3f317218, v218
	v_mul_f32_e32 v218, v218, v219
	v_cndmask_b32_e32 v124, v218, v84, vcc
	global_load_ushort v69, v[28:29], off offset:2560
	s_nop 0
	global_load_ushort v4, v[4:5], off
	s_nop 0
	global_load_dword v28, v[24:25], off
	global_load_dword v29, v[24:25], off offset:2048
	s_nop 0
	global_load_dword v24, v[26:27], off
	global_load_dword v25, v[26:27], off offset:2048
	global_load_ushort v22, v[22:23], off offset:1536
	s_nop 0
	global_load_ushort v20, v[20:21], off offset:512
	s_nop 0
	global_load_ushort v21, v[18:19], off
	s_nop 0
	global_load_ushort v18, v[18:19], off offset:3584
	s_nop 0
	global_load_ushort v19, v[12:13], off offset:3072
	global_load_ushort v23, v[14:15], off offset:2560
	s_nop 0
	global_load_ushort v16, v[16:17], off offset:2048
	s_nop 0
	global_load_ushort v17, v[10:11], off offset:1024
	v_lshlrev_b32_e32 v0, 4, v165
	v_lshl_add_u64 v[10:11], s[28:29], 0, v[0:1]
	v_lshlrev_b32_e32 v0, 7, v164
	v_lshl_add_u64 v[90:91], v[10:11], 0, v[0:1]
	v_add_u32_e32 v10, s14, v82
	v_ashrrev_i32_e32 v11, 31, v10
	v_lshl_add_u64 v[10:11], v[10:11], 2, s[4:5]
	global_load_dword v73, v[10:11], off
	v_lshl_add_u64 v[10:11], s[8:9], 0, v[32:33]
	v_lshl_add_u64 v[12:13], s[12:13], 0, v[32:33]
	global_load_dword v128, v[10:11], off
	global_load_dword v125, v[10:11], off offset:128
	global_load_dword v161, v[10:11], off offset:2048
	global_load_dword v159, v[10:11], off offset:2176
	global_load_dword v129, v[12:13], off
	global_load_dword v127, v[12:13], off offset:128
	global_load_dword v162, v[12:13], off offset:2048
	global_load_dword v160, v[12:13], off offset:2176
	global_load_ushort v0, v[6:7], off offset:1536
	global_load_ushort v30, v[8:9], off offset:1024
	global_load_ushort v33, v[34:35], off offset:512
	s_nop 0
	global_load_ushort v34, v[36:37], off
	global_load_ushort v35, v[36:37], off offset:3584
	s_nop 0
	global_load_ushort v36, v[38:39], off offset:3072
	global_load_ushort v37, v[40:41], off offset:2560
	s_nop 0
	global_load_ushort v38, v[42:43], off offset:2048
	global_load_ushort v39, v[44:45], off offset:1536
	global_load_ushort v40, v[46:47], off offset:1024
	global_load_ushort v41, v[48:49], off offset:512
	s_nop 0
	global_load_ushort v42, v[50:51], off
	global_load_ushort v43, v[50:51], off offset:3584
	global_load_ushort v44, v[52:53], off offset:3072
	global_load_ushort v45, v[54:55], off offset:2560
	global_load_ushort v46, v[56:57], off offset:2048
	global_load_ushort v47, v[58:59], off offset:1536
	global_load_ushort v48, v[60:61], off offset:512
	global_load_ushort v49, v[62:63], off offset:1024
	v_lshlrev_b32_e32 v9, 16, v87
	v_lshlrev_b32_e32 v12, 16, v85
	v_and_b32_e32 v84, 63, v66
	v_lshl_add_u32 v32, v84, 1, s0
	v_add_co_u32_e32 v108, vcc, s60, v90
	v_lshl_add_u64 v[122:123], s[44:45], 0, v[2:3]
	s_nop 0
	v_addc_co_u32_e32 v109, vcc, 0, v91, vcc
	s_mov_b32 s1, 0x11f00000
	v_lshlrev_b64 v[82:83], 3, v[82:83]
	v_readlane_b32 s16, v252, 28
	v_readlane_b32 s17, v252, 29
	v_readlane_b32 s18, v252, 30
	v_readlane_b32 s19, v252, 31
	v_readlane_b32 s15, v254, 44
	s_mov_b64 s[8:9], s[26:27]
	s_waitcnt vmcnt(41)
; template <int MODE>
; __device__ __forceinline__ void lru_unit(const Args& a, int l, int b, int ch, LAS unsigned char* lds) {
;     ...
;     for (int i = 0; i < 35; ++i) { const int t = t0 - 2 + i; xin[i] = (t >= 0 && t < SEQ) ? bf2f(xraw[i]) : 0.f; }
;     if (MODE == 1) {
; #pragma unroll
;         for (int t = 0; t < 32; ++t) gl[t] = gelu_tanh(bf2f(graw[t]));
;     }
;     float xcr[32], hf[32];
; #pragma unroll
;     for (int t = 0; t < 32; ++t) { const float xc = cw0 * xin[t] + cw1 * xin[t + 1] + cw2 * xin[t + 2] + cw3 * xin[t + 3] + cb; xcr[t] = xc; hf[t] = 0.f;
	v_lshlrev_b32_e32 v13, 16, v69
	s_waitcnt vmcnt(40)
	v_lshlrev_b32_e32 v8, 16, v4
	s_waitcnt vmcnt(38)
	v_pk_mul_f32 v[6:7], v[28:29], v[64:65]
	s_nop 0
	v_add_f32_e32 v4, v6, v7
	s_waitcnt vmcnt(36)
	v_pk_mul_f32 v[10:11], v[24:25], v[8:9]
	v_pk_mov_b32 v[6:7], v[64:65], v[8:9] op_sel:[1,0]
	v_add_f32_e32 v4, v10, v4
	v_add_f32_e32 v4, v11, v4
	v_pk_mul_f32 v[6:7], v[28:29], v[6:7]
	v_pk_mul_f32 v[10:11], v[28:29], v[8:9]
	v_pk_mov_b32 v[8:9], v[8:9], v[12:13] op_sel:[1,0]
	v_add_f32_e32 v6, v6, v7
	v_pk_mul_f32 v[14:15], v[24:25], v[8:9]
	v_add_f32_e32 v10, v10, v11
	v_add_f32_e32 v6, v6, v14
	v_add_f32_e32 v50, v6, v15
	v_pk_mul_f32 v[6:7], v[24:25], v[12:13]
	s_waitcnt vmcnt(35)
	v_lshlrev_b32_e32 v11, 16, v22
	v_add_f32_e32 v6, v10, v6
	v_lshlrev_b32_e32 v10, 16, v67
	v_add_f32_e32 v51, v6, v7
	v_pk_mul_f32 v[6:7], v[28:29], v[8:9]
	v_pk_mul_f32 v[8:9], v[28:29], v[12:13]
	v_pk_mov_b32 v[12:13], v[12:13], v[10:11] op_sel:[1,0]
	v_add_f32_e32 v6, v6, v7
	v_pk_mul_f32 v[14:15], v[24:25], v[12:13]
	v_add_f32_e32 v8, v8, v9
	v_add_f32_e32 v6, v6, v14
	v_add_f32_e32 v22, v6, v15
	v_pk_mul_f32 v[6:7], v[24:25], v[10:11]
	s_waitcnt vmcnt(27)
	v_add_f32_e32 v85, v73, v4
	v_add_f32_e32 v6, v8, v6
	v_add_f32_e32 v52, v6, v7
	v_pk_mul_f32 v[6:7], v[28:29], v[12:13]
	v_lshlrev_b32_e32 v13, 16, v20
	v_lshlrev_b32_e32 v12, 16, v17
	v_pk_mul_f32 v[8:9], v[28:29], v[10:11]
	v_pk_mov_b32 v[10:11], v[10:11], v[12:13] op_sel:[1,0]
	v_add_f32_e32 v6, v6, v7
	v_pk_mul_f32 v[14:15], v[24:25], v[10:11]
	v_add_f32_e32 v8, v8, v9
	v_add_f32_e32 v6, v6, v14
	v_add_f32_e32 v17, v6, v15
	v_pk_mul_f32 v[6:7], v[24:25], v[12:13]
	v_add_f32_e32 v130, v73, v51
	v_add_f32_e32 v6, v8, v6
	v_add_f32_e32 v20, v6, v7
	v_pk_mul_f32 v[6:7], v[28:29], v[10:11]
	v_lshlrev_b32_e32 v11, 16, v18
	v_lshlrev_b32_e32 v10, 16, v21
	v_pk_mul_f32 v[8:9], v[28:29], v[12:13]
	v_pk_mov_b32 v[12:13], v[12:13], v[10:11] op_sel:[1,0]
	v_add_f32_e32 v6, v6, v7
	v_pk_mul_f32 v[14:15], v[24:25], v[12:13]
	v_add_f32_e32 v8, v8, v9
	v_add_f32_e32 v6, v6, v14
	v_add_f32_e32 v18, v6, v15
	v_pk_mul_f32 v[6:7], v[24:25], v[10:11]
	v_add_f32_e32 v131, v73, v22
	v_add_f32_e32 v6, v8, v6
	v_add_f32_e32 v21, v6, v7
	v_pk_mul_f32 v[6:7], v[28:29], v[12:13]
	v_lshlrev_b32_e32 v13, 16, v23
	v_lshlrev_b32_e32 v12, 16, v19
	v_pk_mul_f32 v[8:9], v[28:29], v[10:11]
	v_pk_mov_b32 v[10:11], v[10:11], v[12:13] op_sel:[1,0]
	v_add_f32_e32 v6, v6, v7
	v_pk_mul_f32 v[14:15], v[24:25], v[10:11]
	v_add_f32_e32 v8, v8, v9
	v_add_f32_e32 v6, v6, v14
	v_add_f32_e32 v19, v6, v15
	v_pk_mul_f32 v[6:7], v[24:25], v[12:13]
	v_add_f32_e32 v132, v73, v52
	v_add_f32_e32 v6, v8, v6
	v_add_f32_e32 v23, v6, v7
	v_pk_mul_f32 v[6:7], v[28:29], v[10:11]
	s_waitcnt vmcnt(18)
	v_lshlrev_b32_e32 v11, 16, v0
	v_lshlrev_b32_e32 v10, 16, v16
	v_pk_mul_f32 v[8:9], v[28:29], v[12:13]
	v_pk_mov_b32 v[12:13], v[12:13], v[10:11] op_sel:[1,0]
	v_add_f32_e32 v0, v6, v7
	v_pk_mul_f32 v[14:15], v[24:25], v[12:13]
	v_pk_mul_f32 v[6:7], v[24:25], v[10:11]
	v_add_f32_e32 v0, v0, v14
	v_add_f32_e32 v16, v0, v15
	v_add_f32_e32 v0, v8, v9
	v_add_f32_e32 v0, v0, v6
	v_add_f32_e32 v53, v0, v7
	v_pk_mul_f32 v[6:7], v[28:29], v[12:13]
	s_waitcnt vmcnt(16)
	v_lshlrev_b32_e32 v13, 16, v33
	v_lshlrev_b32_e32 v12, 16, v30
	v_pk_mul_f32 v[8:9], v[28:29], v[10:11]
	v_pk_mov_b32 v[10:11], v[10:11], v[12:13] op_sel:[1,0]
	v_add_f32_e32 v0, v6, v7
	v_pk_mul_f32 v[14:15], v[24:25], v[10:11]
	v_pk_mul_f32 v[6:7], v[24:25], v[12:13]
	v_add_f32_e32 v0, v0, v14
	v_add_f32_e32 v33, v0, v15
	v_add_f32_e32 v0, v8, v9
	v_add_f32_e32 v0, v0, v6
	v_add_f32_e32 v54, v0, v7
	v_pk_mul_f32 v[6:7], v[28:29], v[10:11]
	s_waitcnt vmcnt(14)
	v_lshlrev_b32_e32 v11, 16, v35
	v_lshlrev_b32_e32 v10, 16, v34
	v_pk_mul_f32 v[8:9], v[28:29], v[12:13]
	v_pk_mov_b32 v[12:13], v[12:13], v[10:11] op_sel:[1,0]
	v_add_f32_e32 v0, v6, v7
	v_pk_mul_f32 v[14:15], v[24:25], v[12:13]
	v_pk_mul_f32 v[6:7], v[24:25], v[10:11]
	v_add_f32_e32 v0, v0, v14
	v_add_f32_e32 v34, v0, v15
	v_add_f32_e32 v0, v8, v9
	v_add_f32_e32 v0, v0, v6
	v_add_f32_e32 v35, v0, v7
	v_pk_mul_f32 v[6:7], v[28:29], v[12:13]
	s_waitcnt vmcnt(12)
	v_lshlrev_b32_e32 v13, 16, v37
	v_lshlrev_b32_e32 v12, 16, v36
	v_pk_mul_f32 v[8:9], v[28:29], v[10:11]
	v_pk_mov_b32 v[10:11], v[10:11], v[12:13] op_sel:[1,0]
	v_add_f32_e32 v0, v6, v7
	v_pk_mul_f32 v[14:15], v[24:25], v[10:11]
	v_pk_mul_f32 v[6:7], v[24:25], v[12:13]
	v_add_f32_e32 v0, v0, v14
	v_add_f32_e32 v36, v0, v15
	v_add_f32_e32 v0, v8, v9
	v_add_f32_e32 v0, v0, v6
	v_add_f32_e32 v37, v0, v7
	v_pk_mul_f32 v[6:7], v[28:29], v[10:11]
	s_waitcnt vmcnt(10)
	v_lshlrev_b32_e32 v11, 16, v39
	v_lshlrev_b32_e32 v10, 16, v38
	v_pk_mul_f32 v[8:9], v[28:29], v[12:13]
	v_pk_mov_b32 v[12:13], v[12:13], v[10:11] op_sel:[1,0]
	v_add_f32_e32 v0, v6, v7
	v_pk_mul_f32 v[14:15], v[24:25], v[12:13]
	v_pk_mul_f32 v[6:7], v[24:25], v[10:11]
	v_add_f32_e32 v0, v0, v14
	v_add_f32_e32 v38, v0, v15
	v_add_f32_e32 v0, v8, v9
	v_add_f32_e32 v0, v0, v6
	v_add_f32_e32 v39, v0, v7
	v_pk_mul_f32 v[6:7], v[28:29], v[12:13]
	s_waitcnt vmcnt(8)
	v_lshlrev_b32_e32 v13, 16, v41
	v_lshlrev_b32_e32 v12, 16, v40
	v_pk_mul_f32 v[8:9], v[28:29], v[10:11]
	v_pk_mov_b32 v[10:11], v[10:11], v[12:13] op_sel:[1,0]
	v_add_f32_e32 v0, v6, v7
	v_pk_mul_f32 v[14:15], v[24:25], v[10:11]
	v_pk_mul_f32 v[6:7], v[24:25], v[12:13]
	v_add_f32_e32 v0, v0, v14
	v_add_f32_e32 v40, v0, v15
	v_add_f32_e32 v0, v8, v9
	v_add_f32_e32 v0, v0, v6
	v_add_f32_e32 v41, v0, v7
	v_pk_mul_f32 v[6:7], v[28:29], v[10:11]
	s_waitcnt vmcnt(6)
; #define LAS __attribute__((address_space(3)))
; __device__ __forceinline__ unsigned f2bf(float f) { unsigned u = __builtin_bit_cast(unsigned, f); return (u + 0x7fffu + ((u >> 16) & 1u)) >> 16; }
; #define LDS_WAVE_SYNC() asm volatile("s_waitcnt lgkmcnt(0)" ::: "memory")
; template <int MODE>
; __device__ __forceinline__ void lru_unit(const Args& a, int l, int b, int ch, LAS unsigned char* lds) {
;     ...
;     for (int t = 0; t < 32; ++t) { const float xc = cw0 * xin[t] + cw1 * xin[t + 1] + cw2 * xin[t + 2] + cw3 * xin[t + 3] + cb; xcr[t] = xc; hf[t] = 0.f;
;         *(LAS bf16*)(xcb + t * 144 + lane * 2) = (bf16)f2bf(xc); }
; #pragma unroll
;     for (int d = 0; d < 2; ++d)
; #pragma unroll
;         for (int nt = 0; nt < 2; ++nt) { prm[d][nt][0] *= -1.4426950408889634f; prm[d][nt][1] *= -1.4426950408889634f;
;             prm[d][nt][2] = -8.f * 1.4426950408889634f * log1pf(__expf(-prm[d][nt][2])); }
;     LDS_WAVE_SYNC();
	v_lshlrev_b32_e32 v11, 16, v43
	v_lshlrev_b32_e32 v10, 16, v42
	v_pk_mul_f32 v[8:9], v[28:29], v[12:13]
	v_pk_mov_b32 v[12:13], v[12:13], v[10:11] op_sel:[1,0]
	v_add_f32_e32 v0, v6, v7
	v_pk_mul_f32 v[14:15], v[24:25], v[12:13]
	v_pk_mul_f32 v[6:7], v[24:25], v[10:11]
	v_add_f32_e32 v0, v0, v14
	v_add_f32_e32 v42, v0, v15
	v_add_f32_e32 v0, v8, v9
	v_add_f32_e32 v0, v0, v6
	v_add_f32_e32 v43, v0, v7
	v_pk_mul_f32 v[6:7], v[28:29], v[12:13]
	s_waitcnt vmcnt(4)
	v_lshlrev_b32_e32 v13, 16, v45
	v_lshlrev_b32_e32 v12, 16, v44
	v_pk_mul_f32 v[8:9], v[28:29], v[10:11]
	v_pk_mov_b32 v[10:11], v[10:11], v[12:13] op_sel:[1,0]
	v_add_f32_e32 v0, v6, v7
	v_pk_mul_f32 v[14:15], v[24:25], v[10:11]
	v_pk_mul_f32 v[6:7], v[24:25], v[12:13]
	v_add_f32_e32 v0, v0, v14
	v_add_f32_e32 v44, v0, v15
	v_add_f32_e32 v0, v8, v9
	v_add_f32_e32 v0, v0, v6
	v_add_f32_e32 v45, v0, v7
	v_pk_mul_f32 v[6:7], v[28:29], v[10:11]
	s_waitcnt vmcnt(2)
	v_lshlrev_b32_e32 v11, 16, v47
	v_lshlrev_b32_e32 v10, 16, v46
	v_pk_mul_f32 v[8:9], v[28:29], v[12:13]
	v_pk_mov_b32 v[12:13], v[12:13], v[10:11] op_sel:[1,0]
	v_add_f32_e32 v0, v6, v7
	v_pk_mul_f32 v[14:15], v[24:25], v[12:13]
	v_pk_mul_f32 v[6:7], v[24:25], v[10:11]
	v_add_f32_e32 v0, v0, v14
	v_add_f32_e32 v46, v0, v15
	v_add_f32_e32 v0, v8, v9
	v_add_f32_e32 v0, v0, v6
	v_add_f32_e32 v47, v0, v7
	v_pk_mul_f32 v[6:7], v[28:29], v[12:13]
	s_waitcnt vmcnt(0)
	v_lshlrev_b32_e32 v12, 16, v49
	v_lshlrev_b32_e32 v13, 16, v48
	v_pk_mul_f32 v[8:9], v[28:29], v[10:11]
	v_pk_mov_b32 v[10:11], v[10:11], v[12:13] op_sel:[1,0]
	v_add_f32_e32 v0, v6, v7
	v_pk_mul_f32 v[14:15], v[24:25], v[10:11]
	v_pk_mul_f32 v[6:7], v[24:25], v[12:13]
	v_add_f32_e32 v0, v0, v14
	v_add_f32_e32 v14, v0, v15
	v_add_f32_e32 v0, v8, v9
	v_add_f32_e32 v0, v0, v6
	v_add_f32_e32 v12, v0, v7
	v_pk_mul_f32 v[6:7], v[28:29], v[10:11]
	v_mov_b32_e32 v30, v13
	v_pk_mul_f32 v[8:9], v[24:25], v[30:31]
	v_add_f32_e32 v0, v6, v7
	v_add_f32_e32 v0, v0, v8
	v_add_f32_e32 v0, v0, v9
	v_add_f32_e32 v87, v73, v0
	v_bfe_u32 v0, v87, 16, 1
	v_add3_u32 v0, v87, v0, s91
	ds_write_b16_d16_hi v32, v0 offset:4464
	v_bfe_u32 v0, v85, 16, 1
	v_add3_u32 v0, v85, v0, s91
	ds_write_b16_d16_hi v32, v0
	v_add_f32_e32 v0, v73, v50
	v_bfe_u32 v4, v0, 16, 1
	v_add3_u32 v4, v0, v4, s91
	ds_write_b16_d16_hi v32, v4 offset:144
	v_bfe_u32 v4, v130, 16, 1
	v_add3_u32 v4, v130, v4, s91
	ds_write_b16_d16_hi v32, v4 offset:288
	v_bfe_u32 v4, v131, 16, 1
	v_add3_u32 v4, v131, v4, s91
	ds_write_b16_d16_hi v32, v4 offset:432
	v_bfe_u32 v4, v132, 16, 1
	v_add3_u32 v4, v132, v4, s91
	v_add_f32_e32 v133, v73, v17
	ds_write_b16_d16_hi v32, v4 offset:576
	v_bfe_u32 v4, v133, 16, 1
	v_add3_u32 v4, v133, v4, s91
	v_add_f32_e32 v134, v73, v20
	ds_write_b16_d16_hi v32, v4 offset:720
	v_bfe_u32 v4, v134, 16, 1
	v_add3_u32 v4, v134, v4, s91
	v_add_f32_e32 v135, v73, v18
	ds_write_b16_d16_hi v32, v4 offset:864
	v_bfe_u32 v4, v135, 16, 1
	v_add3_u32 v4, v135, v4, s91
	v_add_f32_e32 v136, v73, v21
	ds_write_b16_d16_hi v32, v4 offset:1008
	v_bfe_u32 v4, v136, 16, 1
	v_add3_u32 v4, v136, v4, s91
	v_add_f32_e32 v137, v73, v19
	ds_write_b16_d16_hi v32, v4 offset:1152
	v_bfe_u32 v4, v137, 16, 1
	v_add3_u32 v4, v137, v4, s91
	v_add_f32_e32 v138, v73, v23
	ds_write_b16_d16_hi v32, v4 offset:1296
	v_bfe_u32 v4, v138, 16, 1
	v_add3_u32 v4, v138, v4, s91
	v_add_f32_e32 v139, v73, v16
	ds_write_b16_d16_hi v32, v4 offset:1440
	v_bfe_u32 v4, v139, 16, 1
	v_add3_u32 v4, v139, v4, s91
	v_add_f32_e32 v140, v73, v53
	ds_write_b16_d16_hi v32, v4 offset:1584
	v_bfe_u32 v4, v140, 16, 1
	v_add3_u32 v4, v140, v4, s91
	v_add_f32_e32 v141, v73, v33
	ds_write_b16_d16_hi v32, v4 offset:1728
	v_bfe_u32 v4, v141, 16, 1
	v_add3_u32 v4, v141, v4, s91
	v_add_f32_e32 v142, v73, v54
	ds_write_b16_d16_hi v32, v4 offset:1872
	v_bfe_u32 v4, v142, 16, 1
	v_add3_u32 v4, v142, v4, s91
	v_add_f32_e32 v143, v73, v34
	ds_write_b16_d16_hi v32, v4 offset:2016
	v_bfe_u32 v4, v143, 16, 1
	v_add3_u32 v4, v143, v4, s91
	v_add_f32_e32 v144, v73, v35
	ds_write_b16_d16_hi v32, v4 offset:2160
	v_bfe_u32 v4, v144, 16, 1
	v_add3_u32 v4, v144, v4, s91
	v_add_f32_e32 v145, v73, v36
	ds_write_b16_d16_hi v32, v4 offset:2304
	v_bfe_u32 v4, v145, 16, 1
	v_add3_u32 v4, v145, v4, s91
	v_add_f32_e32 v146, v73, v37
	ds_write_b16_d16_hi v32, v4 offset:2448
	v_bfe_u32 v4, v146, 16, 1
	v_add3_u32 v4, v146, v4, s91
	v_add_f32_e32 v147, v73, v38
	ds_write_b16_d16_hi v32, v4 offset:2592
	v_bfe_u32 v4, v147, 16, 1
	v_add3_u32 v4, v147, v4, s91
	v_add_f32_e32 v148, v73, v39
	ds_write_b16_d16_hi v32, v4 offset:2736
	v_bfe_u32 v4, v148, 16, 1
	v_add3_u32 v4, v148, v4, s91
	v_add_f32_e32 v149, v73, v40
	ds_write_b16_d16_hi v32, v4 offset:2880
	v_bfe_u32 v4, v149, 16, 1
	v_add3_u32 v4, v149, v4, s91
	v_add_f32_e32 v150, v73, v41
	ds_write_b16_d16_hi v32, v4 offset:3024
	v_bfe_u32 v4, v150, 16, 1
	v_add3_u32 v4, v150, v4, s91
	v_add_f32_e32 v151, v73, v42
	ds_write_b16_d16_hi v32, v4 offset:3168
	v_bfe_u32 v4, v151, 16, 1
	v_add3_u32 v4, v151, v4, s91
	v_add_f32_e32 v152, v73, v43
	ds_write_b16_d16_hi v32, v4 offset:3312
	v_bfe_u32 v4, v152, 16, 1
	v_add3_u32 v4, v152, v4, s91
	v_add_f32_e32 v153, v73, v44
	ds_write_b16_d16_hi v32, v4 offset:3456
	v_bfe_u32 v4, v153, 16, 1
	v_add3_u32 v4, v153, v4, s91
	v_add_f32_e32 v154, v73, v45
	ds_write_b16_d16_hi v32, v4 offset:3600
	v_bfe_u32 v4, v154, 16, 1
	v_add3_u32 v4, v154, v4, s91
	v_add_f32_e32 v155, v73, v46
	ds_write_b16_d16_hi v32, v4 offset:3744
	v_bfe_u32 v4, v155, 16, 1
	v_add3_u32 v4, v155, v4, s91
	v_add_f32_e32 v156, v73, v47
	ds_write_b16_d16_hi v32, v4 offset:3888
	v_bfe_u32 v4, v156, 16, 1
	v_add3_u32 v4, v156, v4, s91
	v_add_f32_e32 v157, v73, v14
	ds_write_b16_d16_hi v32, v4 offset:4032
	v_bfe_u32 v4, v157, 16, 1
	v_add3_u32 v4, v157, v4, s91
	v_add_f32_e32 v158, v73, v12
	ds_write_b16_d16_hi v32, v4 offset:4176
	v_bfe_u32 v4, v158, 16, 1
	v_add3_u32 v4, v158, v4, s91
	ds_write_b16_d16_hi v32, v4 offset:4320
	s_waitcnt lgkmcnt(0)
; #define LAS __attribute__((address_space(3)))
; #define MFMA32(a, b, c) __builtin_amdgcn_mfma_f32_32x32x16_bf16((a), (b), (c), 0, 0, 0)
; template <int DIR, int MODE> ...
;     ...
;         const bf16* wr_ = wl + (size_t)((DIR * 8 + w) * 2) * 4096 + (nt * 32 + r32) * 64 + 8 * h;
; #pragma unroll
;         for (int ks = 0; ks < 4; ++ks) {
;             const bf16x8 bR = *(const bf16x8*)(wr_ + 16 * ks), bI = *(const bf16x8*)(wr_ + 4096 + 16 * ks);
;             accR[nt] = MFMA32(af[ks], bR, accR[nt]); accI[nt] = MFMA32(af[ks], bI, accI[nt]); }
;     }
; #pragma unroll
;     for (int nt = 0; nt < 2; ++nt) {
;         const float nba = prm[DIR][nt][0], nbx = prm[DIR][nt][1], k8l = prm[DIR][nt][2];
; #pragma unroll
;         for (int i = 0; i < 16; ++i) {
;             const float d1 = 1.f + __builtin_amdgcn_exp2f(__builtin_fmaf(accR[nt][i], -1.4426950408889634f, nba));
;             const float d2 = 1.f + __builtin_amdgcn_exp2f(__builtin_fmaf(accI[nt][i], -1.4426950408889634f, nbx));
;             const float inv = __builtin_amdgcn_rcpf(d1 * d2), rr = inv * d2, ii = inv * d1;
;             const float av = __builtin_amdgcn_exp2f(k8l * rr);
;             accR[nt][i] = av; accI[nt][i] = __builtin_amdgcn_sqrtf(fmaxf(__builtin_fmaf(-av, av, 1.f), 0.f)) * ii; }
; template <int MODE>
; __device__ __forceinline__ void lru_unit(const Args& a, int l, int b, int ch, LAS unsigned char* lds) {
;     ...
;     for (int ks = 0; ks < 4; ++ks) af[ks] = *(const LAS bf16x8*)(xcb + r32 * 144 + (16 * ks + 8 * h) * 2);
	global_load_dwordx4 v[6:9], v[90:91], off
	global_load_dwordx4 v[10:13], v[108:109], off offset:-4096
	v_add_co_u32_e32 v34, vcc, s59, v90
	s_nop 1
	v_addc_co_u32_e32 v35, vcc, 0, v91, vcc
	global_load_dwordx4 v[14:17], v[90:91], off offset:32
	global_load_dwordx4 v[18:21], v[34:35], off offset:32
	global_load_dwordx4 v[22:25], v[90:91], off offset:64
	global_load_dwordx4 v[26:29], v[34:35], off offset:64
	global_load_dwordx4 v[30:33], v[90:91], off offset:96
	global_load_dwordx4 v[104:107], v[34:35], off offset:96
	v_add_co_u32_e32 v74, vcc, s61, v90
	s_nop 0
	s_nop 0
	v_addc_co_u32_e32 v75, vcc, 0, v91, vcc
	global_load_dwordx4 v[166:169], v[74:75], off
	global_load_dwordx4 v[174:177], v[74:75], off offset:32
	global_load_dwordx4 v[182:185], v[74:75], off offset:64
	v_lshrrev_b32_e32 v5, 1, v66
	v_mul_u32_u24_e32 v4, 0x90, v164
	v_and_b32_e32 v5, 16, v5
	v_add3_u32 v110, s0, v4, v5
	ds_read_b128 v[70:73], v110
	ds_read_b128 v[66:69], v110 offset:32
	global_load_dwordx4 v[170:173], v[74:75], off offset:96
	s_waitcnt vmcnt(11) lgkmcnt(1)
	v_mfma_f32_32x32x16_bf16 v[34:49], v[70:73], v[6:9], 0
	global_load_dwordx4 v[4:7], v[108:109], off
	global_load_dwordx4 v[178:181], v[108:109], off offset:32
	s_waitcnt vmcnt(12)
	v_mfma_f32_32x32x16_bf16 v[50:65], v[70:73], v[10:13], 0
	ds_read_b128 v[74:77], v110 offset:96
	ds_read_b128 v[78:81], v110 offset:64
	s_waitcnt vmcnt(11) lgkmcnt(2)
	v_mfma_f32_32x32x16_bf16 v[34:49], v[66:69], v[14:17], v[34:49]
	v_mul_f32_e32 v97, 0xbfb8aa3b, v128
	global_load_dwordx4 v[186:189], v[108:109], off offset:64
	global_load_dwordx4 v[200:203], v[108:109], off offset:96
	s_waitcnt vmcnt(12)
	v_mfma_f32_32x32x16_bf16 v[50:65], v[66:69], v[18:21], v[50:65]
	v_mul_f32_e32 v99, 0xbfb8aa3b, v129
	v_mul_f32_e32 v93, 0xbfb8aa3b, v127
	v_lshl_add_u64 v[88:89], s[46:47], 0, v[2:3]
	v_mul_f32_e32 v95, 0xbfb8aa3b, v125
	v_add_co_u32_e32 v120, vcc, s1, v88
	s_waitcnt vmcnt(11) lgkmcnt(0)
	v_mfma_f32_32x32x16_bf16 v[34:49], v[78:81], v[22:25], v[34:49]
	v_addc_co_u32_e32 v121, vcc, 0, v89, vcc
	s_mov_b32 s1, 0x11f01000
	v_add_co_u32_e32 v118, vcc, s1, v88
	s_mov_b32 s1, 0x11f02000
	s_nop 0
	v_addc_co_u32_e32 v119, vcc, 0, v89, vcc
	s_waitcnt vmcnt(10)
	v_mfma_f32_32x32x16_bf16 v[50:65], v[78:81], v[26:29], v[50:65]
	v_add_co_u32_e32 v116, vcc, s1, v88
	s_mov_b32 s1, 0x11f03000
	s_nop 0
	v_addc_co_u32_e32 v117, vcc, 0, v89, vcc
	v_add_co_u32_e32 v114, vcc, s1, v88
	s_waitcnt vmcnt(9)
	v_mfma_f32_32x32x16_bf16 v[34:49], v[74:77], v[30:33], v[34:49]
	v_addc_co_u32_e32 v115, vcc, 0, v89, vcc
	s_mov_b32 s1, 0x11f04000
	v_add_co_u32_e32 v112, vcc, s1, v88
	s_mov_b32 s1, 0x11f05000
	s_nop 0
	v_addc_co_u32_e32 v113, vcc, 0, v89, vcc
	s_waitcnt vmcnt(8)
	v_mfma_f32_32x32x16_bf16 v[50:65], v[74:77], v[104:107], v[50:65]
	s_nop 3
	v_fmamk_f32 v34, v34, 0xbfb8aa3b, v97
	v_fmamk_f32 v101, v35, 0xbfb8aa3b, v97
	v_exp_f32_e32 v34, v34
	v_fmamk_f32 v129, v36, 0xbfb8aa3b, v97
	v_fmamk_f32 v38, v38, 0xbfb8aa3b, v97
	v_fmamk_f32 v39, v39, 0xbfb8aa3b, v97
	v_fmamk_f32 v40, v40, 0xbfb8aa3b, v97
	s_nop 0
	v_fmamk_f32 v50, v50, 0xbfb8aa3b, v99
	v_exp_f32_e32 v35, v50
	v_fmamk_f32 v51, v51, 0xbfb8aa3b, v99
	s_waitcnt vmcnt(7)
	v_mfma_f32_32x32x16_bf16 v[18:33], v[70:73], v[166:169], 0
	v_fmamk_f32 v166, v37, 0xbfb8aa3b, v97
	v_add_f32_e64 v34, v34, 1.0
	v_add_f32_e64 v35, v35, 1.0
	v_exp_f32_e32 v37, v51
	v_mul_f32_e32 v36, v34, v35
	v_rcp_f32_e32 v193, v36
	v_exp_f32_e32 v36, v101
	v_mov_b32_e32 v127, v35
	v_fmamk_f32 v41, v41, 0xbfb8aa3b, v97
	v_fmamk_f32 v42, v42, 0xbfb8aa3b, v97
	v_fmamk_f32 v43, v43, 0xbfb8aa3b, v97
	v_fmamk_f32 v44, v44, 0xbfb8aa3b, v97
	v_fmamk_f32 v45, v45, 0xbfb8aa3b, v97
	v_fmamk_f32 v46, v46, 0xbfb8aa3b, v97
	v_fmamk_f32 v167, v47, 0xbfb8aa3b, v97
	v_fmamk_f32 v168, v48, 0xbfb8aa3b, v97
	v_fmac_f32_e32 v97, 0xbfb8aa3b, v49
	v_pk_mul_f32 v[48:49], v[126:127], v[192:193]
	v_pk_add_f32 v[36:37], v[36:37], 1.0 op_sel_hi:[1,0]
	v_mul_f32_e32 v35, v48, v49
	v_exp_f32_e32 v128, v35
	v_mul_f32_e32 v35, v36, v37
	v_rcp_f32_e32 v49, v35
	v_mul_f32_e32 v50, v34, v193
	v_fma_f32 v34, -v128, v128, 1.0 clamp
	v_fmamk_f32 v47, v52, 0xbfb8aa3b, v99
	v_mul_f32_e32 v35, v37, v49
	v_mul_f32_e32 v35, v48, v35
	v_exp_f32_e32 v126, v35
	v_sqrt_f32_e32 v37, v34
	v_exp_f32_e32 v34, v129
	v_exp_f32_e32 v35, v47
	v_fma_f32 v47, -v126, v126, 1.0 clamp
	v_sqrt_f32_e32 v47, v47
	v_pk_add_f32 v[34:35], v[34:35], 1.0 op_sel_hi:[1,0]
	v_fmamk_f32 v52, v53, 0xbfb8aa3b, v99
	v_mul_f32_e32 v51, v34, v35
	v_rcp_f32_e32 v51, v51
	v_mul_f32_e32 v36, v36, v49
	v_mul_f32_e32 v129, v50, v37
	v_mul_f32_e32 v127, v36, v47
	v_exp_f32_e32 v36, v166
	v_exp_f32_e32 v37, v52
	v_mul_f32_e32 v35, v35, v51
	v_mul_f32_e32 v35, v48, v35
	s_waitcnt vmcnt(6)
; #define MFMA32(a, b, c) __builtin_amdgcn_mfma_f32_32x32x16_bf16((a), (b), (c), 0, 0, 0)
; template <int DIR, int MODE> ...
;     ...
;         const bf16* wr_ = wl + (size_t)((DIR * 8 + w) * 2) * 4096 + (nt * 32 + r32) * 64 + 8 * h;
; #pragma unroll
;         for (int ks = 0; ks < 4; ++ks) {
;             const bf16x8 bR = *(const bf16x8*)(wr_ + 16 * ks), bI = *(const bf16x8*)(wr_ + 4096 + 16 * ks);
;             accR[nt] = MFMA32(af[ks], bR, accR[nt]); accI[nt] = MFMA32(af[ks], bI, accI[nt]); }
;     ...
; #pragma unroll
;     for (int nt = 0; nt < 2; ++nt) {
;         const float nba = prm[DIR][nt][0], nbx = prm[DIR][nt][1], k8l = prm[DIR][nt][2];
; #pragma unroll
;         for (int i = 0; i < 16; ++i) {
;             const float d1 = 1.f + __builtin_amdgcn_exp2f(__builtin_fmaf(accR[nt][i], -1.4426950408889634f, nba));
;             const float d2 = 1.f + __builtin_amdgcn_exp2f(__builtin_fmaf(accI[nt][i], -1.4426950408889634f, nbx));
;             const float inv = __builtin_amdgcn_rcpf(d1 * d2), rr = inv * d2, ii = inv * d1;
;             const float av = __builtin_amdgcn_exp2f(k8l * rr);
;             accR[nt][i] = av; accI[nt][i] = __builtin_amdgcn_sqrtf(fmaxf(__builtin_fmaf(-av, av, 1.f), 0.f)) * ii; }
	v_mfma_f32_32x32x16_bf16 v[18:33], v[66:69], v[174:177], v[18:33]
	v_add_f32_e64 v36, v36, 1.0
	v_add_f32_e64 v37, v37, 1.0
	v_fmamk_f32 v176, v62, 0xbfb8aa3b, v99
	v_exp_f32_e32 v62, v35
	v_mul_f32_e32 v35, v36, v37
	v_rcp_f32_e32 v47, v35
	v_fmamk_f32 v53, v54, 0xbfb8aa3b, v99
	v_mul_f32_e32 v49, v34, v51
	v_fma_f32 v34, -v62, v62, 1.0 clamp
	v_mul_f32_e32 v35, v37, v47
	v_mul_f32_e32 v35, v48, v35
	v_exp_f32_e32 v54, v35
	v_sqrt_f32_e32 v37, v34
	v_exp_f32_e32 v34, v38
	v_exp_f32_e32 v35, v53
	v_fma_f32 v38, -v54, v54, 1.0 clamp
	v_sqrt_f32_e32 v38, v38
	v_pk_add_f32 v[34:35], v[34:35], 1.0 op_sel_hi:[1,0]
	v_fmamk_f32 v169, v55, 0xbfb8aa3b, v99
	v_mul_f32_e32 v50, v34, v35
	v_rcp_f32_e32 v51, v50
	v_mul_f32_e32 v36, v36, v47
	v_fmamk_f32 v177, v63, 0xbfb8aa3b, v99
	v_mul_f32_e32 v63, v49, v37
	v_mul_f32_e32 v55, v36, v38
	v_exp_f32_e32 v36, v39
	v_exp_f32_e32 v37, v169
	v_mul_f32_e32 v35, v35, v51
	v_mul_f32_e32 v35, v48, v35
	v_exp_f32_e32 v50, v35
	v_pk_add_f32 v[36:37], v[36:37], 1.0 op_sel_hi:[1,0]
	v_mul_f32_e32 v39, v34, v51
	v_mul_f32_e32 v35, v36, v37
	v_rcp_f32_e32 v38, v35
	v_fma_f32 v34, -v50, v50, 1.0 clamp
	v_fmamk_f32 v56, v56, 0xbfb8aa3b, v99
	v_mul_f32_e32 v35, v37, v38
	v_mul_f32_e32 v35, v48, v35
	v_exp_f32_e32 v52, v35
	v_sqrt_f32_e32 v37, v34
	v_exp_f32_e32 v34, v40
	v_exp_f32_e32 v35, v56
	v_fma_f32 v40, -v52, v52, 1.0 clamp
	v_sqrt_f32_e32 v40, v40
	v_pk_add_f32 v[34:35], v[34:35], 1.0 op_sel_hi:[1,0]
	v_fmamk_f32 v57, v57, 0xbfb8aa3b, v99
	v_mul_f32_e32 v47, v34, v35
	v_rcp_f32_e32 v47, v47
	v_mul_f32_e32 v36, v36, v38
	v_mul_f32_e32 v51, v39, v37
	v_mul_f32_e32 v53, v36, v40
	v_exp_f32_e32 v36, v41
	v_exp_f32_e32 v37, v57
	v_mul_f32_e32 v35, v35, v47
	v_mul_f32_e32 v35, v48, v35
	v_exp_f32_e32 v56, v35
	v_pk_add_f32 v[36:37], v[36:37], 1.0 op_sel_hi:[1,0]
	v_fmamk_f32 v174, v58, 0xbfb8aa3b, v99
	v_mul_f32_e32 v35, v36, v37
	v_rcp_f32_e32 v40, v35
	v_mul_f32_e32 v41, v34, v47
	v_fma_f32 v34, -v56, v56, 1.0 clamp
	v_mul_f32_e32 v35, v37, v40
	v_mul_f32_e32 v35, v48, v35
	v_exp_f32_e32 v58, v35
	v_sqrt_f32_e32 v37, v34
	v_exp_f32_e32 v34, v42
	v_exp_f32_e32 v35, v174
	v_fma_f32 v38, -v58, v58, 1.0 clamp
	v_sqrt_f32_e32 v42, v38
	v_pk_add_f32 v[38:39], v[34:35], 1.0 op_sel_hi:[1,0]
	v_fmamk_f32 v175, v59, 0xbfb8aa3b, v99
	v_mul_f32_e32 v34, v38, v39
	v_rcp_f32_e32 v35, v34
	v_mul_f32_e32 v57, v41, v37
	v_mul_f32_e32 v34, v36, v40
	v_exp_f32_e32 v36, v43
	v_exp_f32_e32 v37, v175
	v_mul_f32_e32 v59, v34, v42
	v_mul_f32_e32 v34, v39, v35
	v_mul_f32_e32 v34, v48, v34
	v_pk_add_f32 v[40:41], v[36:37], 1.0 op_sel_hi:[1,0]
	v_exp_f32_e32 v34, v34
	v_mul_f32_e32 v36, v40, v41
	v_rcp_f32_e32 v37, v36
	v_mul_f32_e32 v35, v38, v35
	v_fma_f32 v36, -v34, v34, 1.0
	v_max_f32_e32 v38, 0, v36
	v_mul_f32_e32 v36, v41, v37
	v_mul_f32_e32 v36, v48, v36
	v_exp_f32_e32 v36, v36
	v_fmamk_f32 v60, v60, 0xbfb8aa3b, v99
	v_sqrt_f32_e32 v41, v38
	v_exp_f32_e32 v38, v44
	v_exp_f32_e32 v39, v60
	v_fma_f32 v42, -v36, v36, 1.0 clamp
	v_sqrt_f32_e32 v44, v42
	v_pk_add_f32 v[42:43], v[38:39], 1.0 op_sel_hi:[1,0]
	v_fmamk_f32 v61, v61, 0xbfb8aa3b, v99
	v_mul_f32_e32 v38, v42, v43
	v_rcp_f32_e32 v39, v38
	v_mul_f32_e32 v35, v35, v41
	v_mul_f32_e32 v37, v40, v37
	v_exp_f32_e32 v40, v45
	v_exp_f32_e32 v41, v61
	v_mul_f32_e32 v38, v43, v39
	v_mul_f32_e32 v37, v37, v44
	v_mul_f32_e32 v38, v48, v38
	v_pk_add_f32 v[44:45], v[40:41], 1.0 op_sel_hi:[1,0]
	v_exp_f32_e32 v38, v38
	v_mul_f32_e32 v40, v44, v45
	v_rcp_f32_e32 v41, v40
	v_mul_f32_e32 v39, v42, v39
	v_fma_f32 v40, -v38, v38, 1.0
	v_max_f32_e32 v42, 0, v40
	v_mul_f32_e32 v40, v45, v41
	v_mul_f32_e32 v40, v48, v40
	v_exp_f32_e32 v40, v40
	v_sqrt_f32_e32 v45, v42
	v_exp_f32_e32 v42, v46
	v_exp_f32_e32 v43, v176
	v_fma_f32 v46, -v40, v40, 1.0 clamp
	s_waitcnt vmcnt(3)
	v_mfma_f32_32x32x16_bf16 v[2:17], v[70:73], v[4:7], 0
	v_sqrt_f32_e32 v49, v46
	v_pk_add_f32 v[46:47], v[42:43], 1.0 op_sel_hi:[1,0]
	v_mul_f32_e32 v39, v39, v45
	v_mul_f32_e32 v42, v46, v47
	v_rcp_f32_e32 v43, v42
	v_mul_f32_e32 v41, v44, v41
	v_exp_f32_e32 v44, v167
	v_exp_f32_e32 v45, v177
	v_mul_f32_e32 v42, v47, v43
	s_waitcnt vmcnt(2)
	v_mfma_f32_32x32x16_bf16 v[2:17], v[66:69], v[178:181], v[2:17]
	v_mul_f32_e32 v42, v48, v42
	v_add_f32_e64 v60, v44, 1.0
	v_add_f32_e64 v61, v45, 1.0
	v_exp_f32_e32 v42, v42
	v_mul_f32_e32 v44, v60, v61
	v_rcp_f32_e32 v45, v44
	v_mul_f32_e32 v43, v46, v43
	v_fma_f32 v44, -v42, v42, 1.0
	v_max_f32_e32 v46, 0, v44
	v_mul_f32_e32 v44, v61, v45
	v_mul_f32_e32 v44, v48, v44
	v_mfma_f32_32x32x16_bf16 v[18:33], v[78:81], v[182:185], v[18:33]
	v_exp_f32_e32 v44, v44
	v_fmamk_f32 v64, v64, 0xbfb8aa3b, v99
	v_mul_f32_e32 v41, v41, v49
	v_sqrt_f32_e32 v49, v46
	v_exp_f32_e32 v46, v168
	v_exp_f32_e32 v47, v64
	v_fma_f32 v61, -v44, v44, 1.0 clamp
	s_waitcnt vmcnt(1)
	v_mfma_f32_32x32x16_bf16 v[2:17], v[78:81], v[186:189], v[2:17]
	v_sqrt_f32_e32 v61, v61
	v_pk_add_f32 v[46:47], v[46:47], 1.0 op_sel_hi:[1,0]
	v_fmac_f32_e32 v99, 0xbfb8aa3b, v65
	v_mul_f32_e32 v64, v46, v47
	v_mul_f32_e32 v45, v60, v45
	v_rcp_f32_e32 v64, v64
	v_mfma_f32_32x32x16_bf16 v[18:33], v[74:77], v[170:173], v[18:33]
	v_mul_f32_e32 v45, v45, v61
	v_exp_f32_e32 v60, v97
	v_exp_f32_e32 v61, v99
	v_mul_f32_e32 v47, v47, v64
	v_mul_f32_e32 v43, v43, v49
	v_mul_f32_e32 v49, v46, v64
	v_pk_add_f32 v[60:61], v[60:61], 1.0 op_sel_hi:[1,0]
	s_waitcnt vmcnt(0)
; #define LAS __attribute__((address_space(3)))
; template <int DIR, int MODE> ...
;     ...
; #pragma unroll
;     for (int nt = 0; nt < 2; ++nt) {
;         const float nba = prm[DIR][nt][0], nbx = prm[DIR][nt][1], k8l = prm[DIR][nt][2];
; #pragma unroll
;         for (int i = 0; i < 16; ++i) {
;             const float d1 = 1.f + __builtin_amdgcn_exp2f(__builtin_fmaf(accR[nt][i], -1.4426950408889634f, nba));
;             const float d2 = 1.f + __builtin_amdgcn_exp2f(__builtin_fmaf(accI[nt][i], -1.4426950408889634f, nbx));
;             const float inv = __builtin_amdgcn_rcpf(d1 * d2), rr = inv * d2, ii = inv * d1;
;             const float av = __builtin_amdgcn_exp2f(k8l * rr);
;             accR[nt][i] = av; accI[nt][i] = __builtin_amdgcn_sqrtf(fmaxf(__builtin_fmaf(-av, av, 1.f), 0.f)) * ii; }
;     }
;     float hc = 0.f, ap = 1.f;
;     if (MODE == 1) hc = ((const float*)(a.ws + WS_CAR))[(size_t)((b * NCH + ch) * 2 + DIR) * LW + c];
; #pragma unroll
;     for (int hh = 0; hh < 2; ++hh) {
;         const int half = DIR == 0 ? hh : 1 - hh;
; #pragma unroll
;         for (int nt = 0; nt < 2; ++nt)
; #pragma unroll
;             for (int i = 0; i < 8; ++i) { const int tt = 8 * (i >> 2) + 4 * h + (i & 3);
;                 f32x2 v; v.x = accR[nt][8 * half + i]; v.y = accI[nt][8 * half + i];
;                 *(LAS f32x2*)(au + (tt * 64 + nt * 32 + r32) * 2) = v; }
	v_mfma_f32_32x32x16_bf16 v[2:17], v[74:77], v[200:203], v[2:17]
	v_mul_f32_e32 v46, v48, v47
	v_mul_f32_e32 v47, v60, v61
	v_rcp_f32_e32 v97, v47
	v_fmamk_f32 v18, v18, 0xbfb8aa3b, v95
	v_exp_f32_e32 v46, v46
	v_exp_f32_e32 v64, v18
	v_mul_f32_e32 v61, v61, v97
	s_nop 4
	v_fmamk_f32 v2, v2, 0xbfb8aa3b, v93
	v_exp_f32_e32 v65, v2
	v_fma_f32 v47, -v46, v46, 1.0 clamp
	v_mul_f32_e32 v48, v48, v61
	v_pk_add_f32 v[64:65], v[64:65], 1.0 op_sel_hi:[1,0]
	v_exp_f32_e32 v48, v48
	v_mul_f32_e32 v18, v64, v65
	v_sqrt_f32_e32 v47, v47
	v_rcp_f32_e32 v193, v18
	v_fma_f32 v2, -v48, v48, 1.0 clamp
	v_mov_b32_e32 v125, v65
	v_mul_f32_e32 v47, v49, v47
	v_mul_f32_e32 v49, v60, v97
	v_pk_mul_f32 v[60:61], v[124:125], v[192:193]
	v_sqrt_f32_e32 v97, v2
	v_mul_f32_e32 v2, v60, v61
	v_exp_f32_e32 v2, v2
	v_fmamk_f32 v18, v19, 0xbfb8aa3b, v95
	v_fmamk_f32 v3, v3, 0xbfb8aa3b, v93
	v_exp_f32_e32 v18, v18
	v_exp_f32_e32 v19, v3
	v_fma_f32 v3, -v2, v2, 1.0 clamp
	v_sqrt_f32_e32 v3, v3
	v_pk_add_f32 v[18:19], v[18:19], 1.0 op_sel_hi:[1,0]
	v_mul_f32_e32 v64, v64, v193
	v_mul_f32_e32 v61, v18, v19
	v_rcp_f32_e32 v61, v61
	v_fmamk_f32 v20, v20, 0xbfb8aa3b, v95
	v_fmamk_f32 v4, v4, 0xbfb8aa3b, v93
	v_mul_f32_e32 v3, v64, v3
	v_exp_f32_e32 v64, v20
	v_exp_f32_e32 v65, v4
	v_mul_f32_e32 v19, v19, v61
	v_mul_f32_e32 v4, v60, v19
	v_mul_f32_e32 v20, v18, v61
	v_exp_f32_e32 v166, v4
	v_pk_add_f32 v[18:19], v[64:65], 1.0 op_sel_hi:[1,0]
	v_fmamk_f32 v5, v5, 0xbfb8aa3b, v93
	v_mul_f32_e32 v4, v18, v19
	v_rcp_f32_e32 v61, v4
	v_fma_f32 v4, -v166, v166, 1.0 clamp
	v_sqrt_f32_e32 v65, v4
	v_mul_f32_e32 v4, v19, v61
	v_mul_f32_e32 v4, v60, v4
	v_exp_f32_e32 v64, v4
	v_fmamk_f32 v4, v21, 0xbfb8aa3b, v95
	v_exp_f32_e32 v4, v4
	v_exp_f32_e32 v5, v5
	v_fma_f32 v19, -v64, v64, 1.0 clamp
	v_sqrt_f32_e32 v19, v19
	v_pk_add_f32 v[4:5], v[4:5], 1.0 op_sel_hi:[1,0]
	v_mul_f32_e32 v49, v49, v97
	v_mul_f32_e32 v21, v4, v5
	v_rcp_f32_e32 v97, v21
	v_mul_f32_e32 v18, v18, v61
	v_mul_f32_e32 v167, v20, v65
	v_mul_f32_e32 v65, v18, v19
	v_fmamk_f32 v18, v22, 0xbfb8aa3b, v95
	v_fmamk_f32 v6, v6, 0xbfb8aa3b, v93
	v_exp_f32_e32 v20, v18
	v_exp_f32_e32 v21, v6
	v_mul_f32_e32 v5, v5, v97
	v_mul_f32_e32 v19, v4, v97
	v_mul_f32_e32 v4, v60, v5
	v_exp_f32_e32 v18, v4
	v_pk_add_f32 v[4:5], v[20:21], 1.0 op_sel_hi:[1,0]
	v_fmamk_f32 v9, v9, 0xbfb8aa3b, v93
	v_mul_f32_e32 v6, v4, v5
	v_rcp_f32_e32 v61, v6
	v_fma_f32 v6, -v18, v18, 1.0 clamp
	v_sqrt_f32_e32 v22, v6
	v_mul_f32_e32 v5, v5, v61
	v_mul_f32_e32 v5, v60, v5
	v_fmamk_f32 v6, v23, 0xbfb8aa3b, v95
	v_exp_f32_e32 v20, v6
	v_exp_f32_e32 v6, v5
	v_fmamk_f32 v5, v7, 0xbfb8aa3b, v93
	v_exp_f32_e32 v21, v5
	v_mul_f32_e32 v19, v19, v22
	v_fma_f32 v5, -v6, v6, 1.0 clamp
	v_pk_add_f32 v[20:21], v[20:21], 1.0 op_sel_hi:[1,0]
	v_sqrt_f32_e32 v5, v5
	v_mul_f32_e32 v7, v20, v21
	v_rcp_f32_e32 v97, v7
	v_fmamk_f32 v7, v24, 0xbfb8aa3b, v95
	v_exp_f32_e32 v22, v7
	v_fmamk_f32 v7, v8, 0xbfb8aa3b, v93
	v_exp_f32_e32 v23, v7
	v_mul_f32_e32 v4, v4, v61
	v_mul_f32_e32 v7, v4, v5
	v_mul_f32_e32 v8, v21, v97
	v_pk_add_f32 v[4:5], v[22:23], 1.0 op_sel_hi:[1,0]
	v_mul_f32_e32 v8, v60, v8
	v_mul_f32_e32 v21, v4, v5
	v_rcp_f32_e32 v21, v21
	v_mul_f32_e32 v24, v20, v97
	v_exp_f32_e32 v8, v8
	v_exp_f32_e32 v23, v9
	v_mul_f32_e32 v5, v5, v21
	v_mul_f32_e32 v5, v60, v5
	v_exp_f32_e32 v20, v5
	v_fma_f32 v5, -v8, v8, 1.0 clamp
	v_sqrt_f32_e32 v5, v5
	v_fma_f32 v22, -v20, v20, 1.0 clamp
	v_sqrt_f32_e32 v61, v22
	v_fmamk_f32 v22, v25, 0xbfb8aa3b, v95
	v_exp_f32_e32 v22, v22
	v_mul_f32_e32 v4, v4, v21
	v_mul_f32_e32 v9, v24, v5
	v_mul_f32_e32 v21, v4, v61
	v_pk_add_f32 v[4:5], v[22:23], 1.0 op_sel_hi:[1,0]
	v_lshlrev_b32_e32 v23, 11, v165
	v_lshlrev_b32_e32 v24, 3, v164
	v_mul_f32_e32 v22, v4, v5
	v_add3_u32 v24, s0, v23, v24
	v_rcp_f32_e32 v22, v22
	v_add_u32_e32 v124, 0x1000, v24
	ds_write2_b64 v124, v[128:129], v[2:3] offset0:64 offset1:96
	v_fmamk_f32 v2, v26, 0xbfb8aa3b, v95
	v_fmamk_f32 v3, v10, 0xbfb8aa3b, v93
	v_exp_f32_e32 v2, v2
	v_exp_f32_e32 v3, v3
	v_mul_f32_e32 v5, v5, v22
	v_mul_f32_e32 v5, v60, v5
	v_exp_f32_e32 v10, v5
	v_mul_f32_e32 v25, v4, v22
	v_pk_add_f32 v[4:5], v[2:3], 1.0 op_sel_hi:[1,0]
	v_fmamk_f32 v13, v13, 0xbfb8aa3b, v93
	v_mul_f32_e32 v2, v4, v5
	v_rcp_f32_e32 v3, v2
	v_fma_f32 v2, -v10, v10, 1.0 clamp
	v_sqrt_f32_e32 v61, v2
	v_mul_f32_e32 v2, v5, v3
	v_fmamk_f32 v5, v27, 0xbfb8aa3b, v95
	v_mul_f32_e32 v2, v60, v2
	v_exp_f32_e32 v22, v5
	v_fmamk_f32 v5, v11, 0xbfb8aa3b, v93
	v_exp_f32_e32 v2, v2
	v_exp_f32_e32 v23, v5
	v_mul_f32_e32 v3, v4, v3
	v_fmamk_f32 v14, v14, 0xbfb8aa3b, v93
	v_fma_f32 v5, -v2, v2, 1.0 clamp
	v_pk_add_f32 v[26:27], v[22:23], 1.0 op_sel_hi:[1,0]
	v_mul_f32_e32 v11, v26, v27
	v_sqrt_f32_e32 v5, v5
	v_rcp_f32_e32 v97, v11
	v_mul_f32_e32 v11, v25, v61
	ds_write2_b64 v124, v[126:127], v[166:167] offset0:128 offset1:160
	v_mul_f32_e32 v3, v3, v5
	v_mul_f32_e32 v4, v27, v97
	v_fmamk_f32 v5, v28, 0xbfb8aa3b, v95
	v_mul_f32_e32 v4, v60, v4
	v_exp_f32_e32 v22, v5
	v_fmamk_f32 v5, v12, 0xbfb8aa3b, v93
	v_exp_f32_e32 v4, v4
	v_exp_f32_e32 v23, v5
	v_exp_f32_e32 v27, v13
	v_add_u32_e32 v126, 0x1800, v24
	v_fma_f32 v5, -v4, v4, 1.0 clamp
	v_pk_add_f32 v[22:23], v[22:23], 1.0 op_sel_hi:[1,0]
	v_mul_f32_e32 v12, v22, v23
	v_sqrt_f32_e32 v5, v5
	v_rcp_f32_e32 v25, v12
	v_mul_f32_e32 v12, v26, v97
	ds_write2_b64 v126, v[54:55], v[18:19] offset1:32
	v_mul_f32_e32 v5, v12, v5
	v_mul_f32_e32 v12, v23, v25
	v_fmamk_f32 v23, v29, 0xbfb8aa3b, v95
	v_exp_f32_e32 v26, v23
	v_mul_f32_e32 v12, v60, v12
	v_exp_f32_e32 v12, v12
	v_mul_f32_e32 v22, v22, v25
	v_pk_add_f32 v[26:27], v[26:27], 1.0 op_sel_hi:[1,0]
	v_exp_f32_e32 v29, v14
	v_mul_f32_e32 v23, v26, v27
	v_fma_f32 v13, -v12, v12, 1.0 clamp
	v_rcp_f32_e32 v28, v23
	v_sqrt_f32_e32 v13, v13
	v_fmamk_f32 v18, v31, 0xbfb8aa3b, v95
	v_mul_f32_e32 v23, v27, v28
	v_mul_f32_e32 v23, v60, v23
	v_mul_f32_e32 v13, v22, v13
	v_mul_f32_e32 v22, v26, v28
	v_exp_f32_e32 v26, v23
	v_fmamk_f32 v23, v30, 0xbfb8aa3b, v95
	v_exp_f32_e32 v28, v23
	v_fmamk_f32 v15, v15, 0xbfb8aa3b, v93
	v_fma_f32 v14, -v26, v26, 1.0 clamp
	v_pk_add_f32 v[28:29], v[28:29], 1.0 op_sel_hi:[1,0]
	v_exp_f32_e32 v18, v18
	v_mul_f32_e32 v23, v28, v29
	v_exp_f32_e32 v19, v15
	v_sqrt_f32_e32 v14, v14
	v_rcp_f32_e32 v23, v23
	v_add_u32_e32 v127, 0x2000, v24
	v_add_u32_e32 v128, 0x2800, v24
	ds_write2_b64 v124, v[62:63], v[64:65] offset0:192 offset1:224
	ds_write2_b64 v127, v[50:51], v[6:7] offset0:64 offset1:96
	ds_write2_b64 v127, v[52:53], v[8:9] offset0:128 offset1:160
	ds_write2_b64 v127, v[56:57], v[20:21] offset0:192 offset1:224
	ds_write2_b64 v128, v[58:59], v[10:11] offset1:32
	v_lshl_add_u32 v125, v84, 3, s0
	v_pk_add_f32 v[18:19], v[18:19], 1.0 op_sel_hi:[1,0]
	s_waitcnt lgkmcnt(0)
; __device__ __forceinline__ unsigned cvt_pk_bf16(float lo, float hi) { unsigned r; asm volatile("v_cvt_pk_bf16_f32 %0, %1, %2" : "=v"(r) : "v"(lo), "v"(hi)); return r; }
; #define LAS __attribute__((address_space(3)))
; #define LDS_WAVE_SYNC() asm volatile("s_waitcnt lgkmcnt(0)" ::: "memory")
; template <int DIR, int MODE> ...
;     ...
; #pragma unroll
;     for (int nt = 0; nt < 2; ++nt) {
;         const float nba = prm[DIR][nt][0], nbx = prm[DIR][nt][1], k8l = prm[DIR][nt][2];
; #pragma unroll
;         for (int i = 0; i < 16; ++i) {
;             const float d1 = 1.f + __builtin_amdgcn_exp2f(__builtin_fmaf(accR[nt][i], -1.4426950408889634f, nba));
;             const float d2 = 1.f + __builtin_amdgcn_exp2f(__builtin_fmaf(accI[nt][i], -1.4426950408889634f, nbx));
;             const float inv = __builtin_amdgcn_rcpf(d1 * d2), rr = inv * d2, ii = inv * d1;
;             const float av = __builtin_amdgcn_exp2f(k8l * rr);
;             accR[nt][i] = av; accI[nt][i] = __builtin_amdgcn_sqrtf(fmaxf(__builtin_fmaf(-av, av, 1.f), 0.f)) * ii; }
;     ...
;         LDS_WAVE_SYNC();
; #pragma unroll
;         for (int s = 0; s < 16; ++s) {
;             const int tt = DIR == 0 ? s : 15 - s, t = half * 16 + tt;
;             const f32x2 v = *(const LAS f32x2*)(au + (tt * 64 + lane) * 2);
;             hc = v.x * hc + v.y * xcr[t];
;             if (MODE == 0) { ap *= v.x;
;                 ((unsigned*)(a.ws + WS_HP))[((size_t)DIR * T + (size_t)b * SEQ + ch * 32 + t) * LW + c] = pg8::cvt_pk_bf16(hc, ap); }
	v_mul_f32_e32 v27, v22, v14
	v_mul_f32_e32 v14, v29, v23
	v_mul_f32_e32 v22, v28, v23
	v_mul_f32_e32 v23, v18, v19
	ds_read_b64 v[8:9], v125 offset:4608
	v_rcp_f32_e32 v23, v23
	v_mov_b32_e32 v84, v1
	v_mul_f32_e32 v14, v60, v14
	v_exp_f32_e32 v14, v14
	v_mul_f32_e32 v7, v18, v23
	s_waitcnt lgkmcnt(0)
	v_mul_f32_e32 v18, v85, v9
	v_mul_f32_e32 v6, v19, v23
	v_pk_fma_f32 v[18:19], v[84:85], v[8:9], v[18:19] op_sel_hi:[1,1,0]
	v_fma_f32 v15, -v14, v14, 1.0 clamp
	v_cvt_pk_bf16_f32 v19, v18, v8
	ds_read_b64 v[20:21], v125 offset:5120
	v_mul_f32_e32 v6, v60, v6
	v_exp_f32_e32 v6, v6
	v_fmamk_f32 v11, v16, 0xbfb8aa3b, v93
	global_store_dword v[122:123], v19, off
	v_mov_b32_e32 v19, v0
	s_waitcnt lgkmcnt(0)
	v_mul_f32_e32 v16, v0, v21
	v_sqrt_f32_e32 v15, v15
	v_pk_fma_f32 v[18:19], v[18:19], v[20:21], v[16:17] op_sel_hi:[1,1,0]
	v_pk_mul_f32 v[8:9], v[8:9], v[20:21]
	v_fma_f32 v10, -v6, v6, 1.0
	v_cvt_pk_bf16_f32 v16, v18, v8
	ds_read_b64 v[20:21], v125 offset:5632
	v_mul_f32_e32 v15, v22, v15
	v_max_f32_e32 v22, 0, v10
	v_fmamk_f32 v10, v32, 0xbfb8aa3b, v95
	v_exp_f32_e32 v10, v10
	v_exp_f32_e32 v11, v11
	global_store_dword v[120:121], v16, off offset:2048
	v_mov_b32_e32 v19, v130
	s_waitcnt lgkmcnt(0)
	v_mul_f32_e32 v16, v130, v21
	v_pk_fma_f32 v[18:19], v[18:19], v[20:21], v[16:17] op_sel_hi:[1,1,0]
	v_pk_mul_f32 v[8:9], v[8:9], v[20:21]
	v_pk_add_f32 v[10:11], v[10:11], 1.0 op_sel_hi:[1,0]
	v_cvt_pk_bf16_f32 v16, v18, v8
	ds_read_b64 v[20:21], v125 offset:6144
	v_mul_f32_e32 v19, v10, v11
	v_rcp_f32_e32 v23, v19
	global_store_dword v[116:117], v16, off offset:-4096
	v_mov_b32_e32 v19, v131
	s_waitcnt lgkmcnt(0)
	v_mul_f32_e32 v16, v131, v21
	v_pk_fma_f32 v[18:19], v[18:19], v[20:21], v[16:17] op_sel_hi:[1,1,0]
	v_pk_mul_f32 v[8:9], v[8:9], v[20:21]
	v_mov_b32_e32 v19, v132
	v_cvt_pk_bf16_f32 v16, v18, v8
	ds_read_b64 v[20:21], v125 offset:6656
	global_store_dword v[118:119], v16, off offset:2048
	v_sqrt_f32_e32 v22, v22
	v_mul_f32_e32 v11, v11, v23
	v_mul_f32_e32 v11, v60, v11
	s_waitcnt lgkmcnt(0)
	v_mul_f32_e32 v16, v132, v21
	v_pk_fma_f32 v[18:19], v[18:19], v[20:21], v[16:17] op_sel_hi:[1,1,0]
	v_pk_mul_f32 v[8:9], v[8:9], v[20:21]
	v_mul_f32_e32 v7, v7, v22
	v_cvt_pk_bf16_f32 v19, v18, v8
	ds_read_b64 v[20:21], v125 offset:7168
	global_store_dword v[116:117], v19, off
	v_mov_b32_e32 v19, v133
	v_exp_f32_e32 v16, v11
	v_fmac_f32_e32 v95, 0xbfb8aa3b, v33
	s_waitcnt lgkmcnt(0)
	v_mul_f32_e32 v22, v133, v21
	v_pk_fma_f32 v[18:19], v[18:19], v[20:21], v[22:23] op_sel_hi:[1,1,0]
	v_pk_mul_f32 v[8:9], v[8:9], v[20:21]
	v_mul_f32_e32 v23, v10, v23
	v_cvt_pk_bf16_f32 v11, v18, v8
	ds_read_b64 v[20:21], v125 offset:7680
	v_mov_b32_e32 v19, v134
	global_store_dword v[116:117], v11, off offset:2048
	v_fmac_f32_e32 v93, 0xbfb8aa3b, v17
	v_add_co_u32_e32 v110, vcc, s1, v88
	s_waitcnt lgkmcnt(0)
	v_mul_f32_e32 v10, v134, v21
	v_pk_fma_f32 v[10:11], v[18:19], v[20:21], v[10:11] op_sel_hi:[1,1,0]
	v_pk_mul_f32 v[8:9], v[8:9], v[20:21]
	v_exp_f32_e32 v20, v95
	v_cvt_pk_bf16_f32 v11, v10, v8
	ds_read_b64 v[18:19], v125 offset:8192
	global_store_dword v[112:113], v11, off offset:-4096
	v_mov_b32_e32 v11, v135
	v_exp_f32_e32 v21, v93
	v_addc_co_u32_e32 v111, vcc, 0, v89, vcc
	s_waitcnt lgkmcnt(0)
	v_mul_f32_e32 v22, v135, v19
	v_pk_fma_f32 v[10:11], v[10:11], v[18:19], v[22:23] op_sel_hi:[1,1,0]
	v_pk_mul_f32 v[8:9], v[8:9], v[18:19]
	v_pk_add_f32 v[20:21], v[20:21], 1.0 op_sel_hi:[1,0]
	v_cvt_pk_bf16_f32 v11, v10, v8
	ds_read_b64 v[18:19], v125 offset:8704
	global_store_dword v[114:115], v11, off offset:2048
	v_mov_b32_e32 v11, v136
	s_mov_b32 s1, 0x11f06000
	v_add_co_u32_e32 v108, vcc, s1, v88
	s_waitcnt lgkmcnt(0)
	v_mul_f32_e32 v22, v136, v19
	v_pk_fma_f32 v[10:11], v[10:11], v[18:19], v[22:23] op_sel_hi:[1,1,0]
	v_pk_mul_f32 v[8:9], v[8:9], v[18:19]
	v_addc_co_u32_e32 v109, vcc, 0, v89, vcc
	v_cvt_pk_bf16_f32 v11, v10, v8
	ds_read_b64 v[18:19], v125 offset:9216
	global_store_dword v[112:113], v11, off
	v_mov_b32_e32 v11, v137
	v_fma_f32 v24, -v16, v16, 1.0
	v_max_f32_e32 v17, 0, v24
	s_waitcnt lgkmcnt(0)
	v_mul_f32_e32 v22, v137, v19
	v_pk_fma_f32 v[10:11], v[10:11], v[18:19], v[22:23] op_sel_hi:[1,1,0]
	v_pk_mul_f32 v[8:9], v[8:9], v[18:19]
	v_mul_f32_e32 v22, v20, v21
	v_cvt_pk_bf16_f32 v11, v10, v8
	ds_read_b64 v[18:19], v125 offset:9728
	v_rcp_f32_e32 v25, v22
	global_store_dword v[112:113], v11, off offset:2048
	v_mov_b32_e32 v11, v138
	s_mov_b32 s1, 0x11f07000
	s_waitcnt lgkmcnt(0)
	v_mul_f32_e32 v22, v138, v19
	v_pk_fma_f32 v[10:11], v[10:11], v[18:19], v[22:23] op_sel_hi:[1,1,0]
	v_pk_mul_f32 v[8:9], v[8:9], v[18:19]
	v_mul_f32_e32 v21, v21, v25
	v_cvt_pk_bf16_f32 v11, v10, v8
	ds_read_b64 v[18:19], v125 offset:10240
	global_store_dword v[108:109], v11, off offset:-4096
	v_mov_b32_e32 v11, v139
	v_mul_f32_e32 v21, v60, v21
	v_add_co_u32_e32 v106, vcc, s1, v88
	s_waitcnt lgkmcnt(0)
	v_mul_f32_e32 v22, v139, v19
	v_pk_fma_f32 v[10:11], v[10:11], v[18:19], v[22:23] op_sel_hi:[1,1,0]
	v_pk_mul_f32 v[8:9], v[8:9], v[18:19]
	v_exp_f32_e32 v22, v21
	v_cvt_pk_bf16_f32 v11, v10, v8
	ds_read_b64 v[18:19], v125 offset:10752
	global_store_dword v[110:111], v11, off offset:2048
	v_mov_b32_e32 v11, v140
	v_fma_f32 v21, -v22, v22, 1.0 clamp
	s_waitcnt lgkmcnt(0)
	v_mul_f32_e32 v24, v140, v19
	v_pk_fma_f32 v[10:11], v[10:11], v[18:19], v[24:25] op_sel_hi:[1,1,0]
	v_pk_mul_f32 v[8:9], v[8:9], v[18:19]
	v_sqrt_f32_e32 v17, v17
	v_cvt_pk_bf16_f32 v11, v10, v8
	ds_read_b64 v[18:19], v125 offset:11264
	global_store_dword v[108:109], v11, off
	v_mov_b32_e32 v11, v141
	v_sqrt_f32_e32 v21, v21
	v_addc_co_u32_e32 v107, vcc, 0, v89, vcc
	s_waitcnt lgkmcnt(0)
; __device__ __forceinline__ unsigned cvt_pk_bf16(float lo, float hi) { unsigned r; asm volatile("v_cvt_pk_bf16_f32 %0, %1, %2" : "=v"(r) : "v"(lo), "v"(hi)); return r; }
; #define LAS __attribute__((address_space(3)))
; #define LDS_WAVE_SYNC() asm volatile("s_waitcnt lgkmcnt(0)" ::: "memory")
; template <int DIR, int MODE> ...
;     ...
; #pragma unroll
;     for (int hh = 0; hh < 2; ++hh) {
;         const int half = DIR == 0 ? hh : 1 - hh;
; #pragma unroll
;         for (int nt = 0; nt < 2; ++nt)
; #pragma unroll
;             for (int i = 0; i < 8; ++i) { const int tt = 8 * (i >> 2) + 4 * h + (i & 3);
;                 f32x2 v; v.x = accR[nt][8 * half + i]; v.y = accI[nt][8 * half + i];
;                 *(LAS f32x2*)(au + (tt * 64 + nt * 32 + r32) * 2) = v; }
;         LDS_WAVE_SYNC();
; #pragma unroll
;         for (int s = 0; s < 16; ++s) {
;             const int tt = DIR == 0 ? s : 15 - s, t = half * 16 + tt;
;             const f32x2 v = *(const LAS f32x2*)(au + (tt * 64 + lane) * 2);
;             hc = v.x * hc + v.y * xcr[t];
;             if (MODE == 0) { ap *= v.x;
;                 ((unsigned*)(a.ws + WS_HP))[((size_t)DIR * T + (size_t)b * SEQ + ch * 32 + t) * LW + c] = pg8::cvt_pk_bf16(hc, ap); }
;             if (MODE == 1) { if (DIR == 0) hf[t] = hc; else hf[t] = gl[t] * (hf[t] + hc); }
;         }
	v_mul_f32_e32 v24, v141, v19
	v_pk_fma_f32 v[10:11], v[10:11], v[18:19], v[24:25] op_sel_hi:[1,1,0]
	v_pk_mul_f32 v[8:9], v[8:9], v[18:19]
	s_mov_b32 s1, 0x11f08000
	v_cvt_pk_bf16_f32 v11, v10, v8
	ds_read_b64 v[18:19], v125 offset:11776
	global_store_dword v[108:109], v11, off offset:2048
	v_mov_b32_e32 v11, v142
	v_add_co_u32_e32 v104, vcc, s1, v88
	s_waitcnt lgkmcnt(0)
	v_mul_f32_e32 v24, v142, v19
	v_pk_fma_f32 v[10:11], v[10:11], v[18:19], v[24:25] op_sel_hi:[1,1,0]
	v_pk_mul_f32 v[8:9], v[8:9], v[18:19]
	v_addc_co_u32_e32 v105, vcc, 0, v89, vcc
	v_cvt_pk_bf16_f32 v11, v10, v8
	ds_read_b64 v[18:19], v125 offset:12288
	v_mul_f32_e32 v20, v20, v25
	v_mul_f32_e32 v17, v23, v17
	v_mul_f32_e32 v23, v20, v21
	global_store_dword v[104:105], v11, off offset:-4096
	v_mov_b32_e32 v11, v143
	s_waitcnt lgkmcnt(0)
	v_mul_f32_e32 v20, v143, v19
	v_pk_fma_f32 v[10:11], v[10:11], v[18:19], v[20:21] op_sel_hi:[1,1,0]
	v_pk_mul_f32 v[8:9], v[8:9], v[18:19]
	v_cvt_pk_bf16_f32 v11, v10, v8
	global_store_dword v[106:107], v11, off offset:2048
	s_waitcnt lgkmcnt(0)
	ds_write2_b64 v124, v[34:35], v[2:3] offset0:64 offset1:96
	ds_write2_b64 v124, v[36:37], v[4:5] offset0:128 offset1:160
	ds_write2_b64 v124, v[38:39], v[12:13] offset0:192 offset1:224
	ds_write2_b64 v126, v[40:41], v[26:27] offset1:32
	ds_write2_b64 v127, v[42:43], v[14:15] offset0:64 offset1:96
	ds_write2_b64 v127, v[44:45], v[6:7] offset0:128 offset1:160
	ds_write2_b64 v127, v[46:47], v[16:17] offset0:192 offset1:224
	ds_write2_b64 v128, v[48:49], v[22:23] offset1:32
	s_waitcnt lgkmcnt(0)
	ds_read_b64 v[2:3], v125 offset:4608
	v_mov_b32_e32 v11, v144
	s_mov_b32 s1, 0x11f0a000
	s_waitcnt lgkmcnt(0)
	v_mul_f32_e32 v6, v144, v3
	v_pk_fma_f32 v[6:7], v[10:11], v[2:3], v[6:7] op_sel_hi:[1,1,0]
	v_pk_mul_f32 v[2:3], v[8:9], v[2:3]
	v_cvt_pk_bf16_f32 v7, v6, v2
	ds_read_b64 v[8:9], v125 offset:5120
	global_store_dword v[104:105], v7, off
	v_mov_b32_e32 v7, v145
	v_add_co_u32_e32 v10, vcc, s1, v88
	s_waitcnt lgkmcnt(0)
	v_mul_f32_e32 v4, v145, v9
	v_pk_fma_f32 v[6:7], v[6:7], v[8:9], v[4:5] op_sel_hi:[1,1,0]
	v_pk_mul_f32 v[2:3], v[2:3], v[8:9]
	v_mov_b32_e32 v7, v146
	v_cvt_pk_bf16_f32 v4, v6, v2
	ds_read_b64 v[8:9], v125 offset:5632
	global_store_dword v[104:105], v4, off offset:2048
	v_addc_co_u32_e32 v11, vcc, 0, v89, vcc
	s_mov_b32 s0, 0x11f09000
	s_waitcnt lgkmcnt(0)
	v_mul_f32_e32 v4, v146, v9
	v_pk_fma_f32 v[6:7], v[6:7], v[8:9], v[4:5] op_sel_hi:[1,1,0]
	v_pk_mul_f32 v[2:3], v[2:3], v[8:9]
	v_mov_b32_e32 v7, v147
	v_cvt_pk_bf16_f32 v4, v6, v2
	ds_read_b64 v[8:9], v125 offset:6144
	global_store_dword v[10:11], v4, off offset:-4096
	v_add_co_u32_e32 v12, vcc, s0, v88
	s_mov_b32 s1, 0x11f0c000
	s_waitcnt lgkmcnt(0)
	v_mul_f32_e32 v4, v147, v9
	v_pk_fma_f32 v[6:7], v[6:7], v[8:9], v[4:5] op_sel_hi:[1,1,0]
	v_pk_mul_f32 v[2:3], v[2:3], v[8:9]
	v_addc_co_u32_e32 v13, vcc, 0, v89, vcc
	v_cvt_pk_bf16_f32 v4, v6, v2
	ds_read_b64 v[8:9], v125 offset:6656
	global_store_dword v[12:13], v4, off offset:2048
	v_mov_b32_e32 v7, v148
	s_mov_b32 s0, 0x11f0b000
	s_waitcnt lgkmcnt(0)
	v_mul_f32_e32 v4, v148, v9
	v_pk_fma_f32 v[6:7], v[6:7], v[8:9], v[4:5] op_sel_hi:[1,1,0]
	v_pk_mul_f32 v[2:3], v[2:3], v[8:9]
	v_cvt_pk_bf16_f32 v4, v6, v2
	ds_read_b64 v[8:9], v125 offset:7168
	global_store_dword v[10:11], v4, off
	v_mov_b32_e32 v7, v149
	s_waitcnt lgkmcnt(0)
	v_mul_f32_e32 v4, v149, v9
	v_pk_fma_f32 v[4:5], v[6:7], v[8:9], v[4:5] op_sel_hi:[1,1,0]
	v_pk_mul_f32 v[2:3], v[2:3], v[8:9]
	s_nop 0
	v_cvt_pk_bf16_f32 v5, v4, v2
	ds_read_b64 v[6:7], v125 offset:7680
	global_store_dword v[10:11], v5, off offset:2048
	v_mov_b32_e32 v5, v150
	s_waitcnt lgkmcnt(0)
	v_mul_f32_e32 v8, v150, v7
	v_pk_fma_f32 v[4:5], v[4:5], v[6:7], v[8:9] op_sel_hi:[1,1,0]
	v_pk_mul_f32 v[2:3], v[2:3], v[6:7]
	v_add_co_u32_e32 v8, vcc, s1, v88
	v_cvt_pk_bf16_f32 v5, v4, v2
	ds_read_b64 v[6:7], v125 offset:8192
	s_nop 0
	v_addc_co_u32_e32 v9, vcc, 0, v89, vcc
	global_store_dword v[8:9], v5, off offset:-4096
	v_mov_b32_e32 v5, v151
	s_waitcnt lgkmcnt(0)
	v_mul_f32_e32 v10, v151, v7
	v_pk_fma_f32 v[4:5], v[4:5], v[6:7], v[10:11] op_sel_hi:[1,1,0]
	v_pk_mul_f32 v[2:3], v[2:3], v[6:7]
	v_add_co_u32_e32 v10, vcc, s0, v88
	v_cvt_pk_bf16_f32 v5, v4, v2
	ds_read_b64 v[6:7], v125 offset:8704
	s_nop 0
	v_addc_co_u32_e32 v11, vcc, 0, v89, vcc
	global_store_dword v[10:11], v5, off offset:2048
	v_mov_b32_e32 v5, v152
	s_waitcnt lgkmcnt(0)
	v_mul_f32_e32 v10, v152, v7
	v_pk_fma_f32 v[4:5], v[4:5], v[6:7], v[10:11] op_sel_hi:[1,1,0]
	v_pk_mul_f32 v[2:3], v[2:3], v[6:7]
	v_cvt_pk_bf16_f32 v5, v4, v2
	ds_read_b64 v[6:7], v125 offset:9216
	global_store_dword v[8:9], v5, off
	v_mov_b32_e32 v5, v153
	s_mov_b32 s1, 0x11f0e000
	s_waitcnt lgkmcnt(0)
	v_mul_f32_e32 v10, v153, v7
	v_pk_fma_f32 v[4:5], v[4:5], v[6:7], v[10:11] op_sel_hi:[1,1,0]
	v_pk_mul_f32 v[2:3], v[2:3], v[6:7]
	s_mov_b32 s0, 0x11f0d000
	v_cvt_pk_bf16_f32 v5, v4, v2
	ds_read_b64 v[6:7], v125 offset:9728
	global_store_dword v[8:9], v5, off offset:2048
	v_mov_b32_e32 v5, v154
	s_waitcnt lgkmcnt(0)
	v_mul_f32_e32 v8, v154, v7
	v_pk_fma_f32 v[4:5], v[4:5], v[6:7], v[8:9] op_sel_hi:[1,1,0]
	v_pk_mul_f32 v[2:3], v[2:3], v[6:7]
	v_add_co_u32_e32 v8, vcc, s1, v88
	v_cvt_pk_bf16_f32 v5, v4, v2
	ds_read_b64 v[6:7], v125 offset:10240
	s_nop 0
	v_addc_co_u32_e32 v9, vcc, 0, v89, vcc
	global_store_dword v[8:9], v5, off offset:-4096
	v_mov_b32_e32 v5, v155
	s_waitcnt lgkmcnt(0)
	v_mul_f32_e32 v10, v155, v7
	v_pk_fma_f32 v[4:5], v[4:5], v[6:7], v[10:11] op_sel_hi:[1,1,0]
	v_pk_mul_f32 v[2:3], v[2:3], v[6:7]
	v_add_co_u32_e32 v10, vcc, s0, v88
	v_cvt_pk_bf16_f32 v5, v4, v2
	ds_read_b64 v[6:7], v125 offset:10752
	s_nop 0
	v_addc_co_u32_e32 v11, vcc, 0, v89, vcc
	global_store_dword v[10:11], v5, off offset:2048
	v_mov_b32_e32 v5, v156
	s_waitcnt lgkmcnt(0)
; #define LAS __attribute__((address_space(3)))
; template <int DIR, int MODE> ...
;     const int r32 = lane & 31, h = lane >> 5, c = w * 64 + lane;
;     f32x16 accR[2], accI[2];
; #pragma unroll
;     for (int nt = 0; nt < 2; ++nt) {
; #pragma unroll
;         for (int i = 0; i < 16; ++i) { accR[nt][i] = 0.f; accI[nt][i] = 0.f; }
;         const bf16* wr_ = wl + (size_t)((DIR * 8 + w) * 2) * 4096 + (nt * 32 + r32) * 64 + 8 * h;
; #pragma unroll
;         for (int ks = 0; ks < 4; ++ks) {
;             const bf16x8 bR = *(const bf16x8*)(wr_ + 16 * ks), bI = *(const bf16x8*)(wr_ + 4096 + 16 * ks);
;             accR[nt] = MFMA32(af[ks], bR, accR[nt]); accI[nt] = MFMA32(af[ks], bI, accI[nt]); }
;     }
; #pragma unroll
;     for (int nt = 0; nt < 2; ++nt) {
;         const float nba = prm[DIR][nt][0], nbx = prm[DIR][nt][1], k8l = prm[DIR][nt][2];
; #pragma unroll
;         for (int i = 0; i < 16; ++i) {
;             const float d1 = 1.f + __builtin_amdgcn_exp2f(__builtin_fmaf(accR[nt][i], -1.4426950408889634f, nba));
;             const float d2 = 1.f + __builtin_amdgcn_exp2f(__builtin_fmaf(accI[nt][i], -1.4426950408889634f, nbx));
;             const float inv = __builtin_amdgcn_rcpf(d1 * d2), rr = inv * d2, ii = inv * d1;
;             const float av = __builtin_amdgcn_exp2f(k8l * rr);
;             accR[nt][i] = av; accI[nt][i] = __builtin_amdgcn_sqrtf(fmaxf(__builtin_fmaf(-av, av, 1.f), 0.f)) * ii; }
;     }
;     float hc = 0.f, ap = 1.f;
;     if (MODE == 1) hc = ((const float*)(a.ws + WS_CAR))[(size_t)((b * NCH + ch) * 2 + DIR) * LW + c];
; #pragma unroll
;     for (int hh = 0; hh < 2; ++hh) {
;         const int half = DIR == 0 ? hh : 1 - hh;
; #pragma unroll
;         for (int nt = 0; nt < 2; ++nt)
; #pragma unroll
;             for (int i = 0; i < 8; ++i) { const int tt = 8 * (i >> 2) + 4 * h + (i & 3);
;                 f32x2 v; v.x = accR[nt][8 * half + i]; v.y = accI[nt][8 * half + i];
;                 *(LAS f32x2*)(au + (tt * 64 + nt * 32 + r32) * 2) = v; }
;         LDS_WAVE_SYNC();
; #pragma unroll
;         for (int s = 0; s < 16; ++s) {
;             const int tt = DIR == 0 ? s : 15 - s, t = half * 16 + tt;
;             const f32x2 v = *(const LAS f32x2*)(au + (tt * 64 + lane) * 2);
;             hc = v.x * hc + v.y * xcr[t];
;             if (MODE == 0) { ap *= v.x;
	v_mul_f32_e32 v10, v156, v7
	v_pk_fma_f32 v[4:5], v[4:5], v[6:7], v[10:11] op_sel_hi:[1,1,0]
	v_pk_mul_f32 v[2:3], v[2:3], v[6:7]
	s_mov_b32 s0, 0x11f0f000
	v_cvt_pk_bf16_f32 v5, v4, v2
	ds_read_b64 v[6:7], v125 offset:11264
	global_store_dword v[8:9], v5, off
	v_mov_b32_e32 v5, v157
	v_lshl_add_u64 v[10:11], s[42:43], 0, v[82:83]
	s_waitcnt lgkmcnt(0)
	v_mul_f32_e32 v12, v157, v7
	v_pk_fma_f32 v[4:5], v[4:5], v[6:7], v[12:13] op_sel_hi:[1,1,0]
	v_pk_mul_f32 v[2:3], v[2:3], v[6:7]
	v_add_co_u32_e32 v12, vcc, s0, v88
	v_cvt_pk_bf16_f32 v5, v4, v2
	ds_read_b64 v[6:7], v125 offset:11776
	global_store_dword v[8:9], v5, off offset:2048
	v_mov_b32_e32 v5, v158
	v_addc_co_u32_e32 v13, vcc, 0, v89, vcc
	s_waitcnt lgkmcnt(0)
	v_mul_f32_e32 v8, v158, v7
	v_pk_fma_f32 v[4:5], v[4:5], v[6:7], v[8:9] op_sel_hi:[1,1,0]
	v_pk_mul_f32 v[2:3], v[2:3], v[6:7]
	s_mov_b32 s0, 0x21000
	v_cvt_pk_bf16_f32 v5, v4, v2
	ds_read_b64 v[6:7], v125 offset:12288
	global_store_dword v[12:13], v5, off
	v_mov_b32_e32 v5, v87
	v_add_co_u32_e32 v98, vcc, s0, v90
	s_waitcnt lgkmcnt(0)
	v_mul_f32_e32 v8, v87, v7
	v_pk_mul_f32 v[2:3], v[2:3], v[6:7]
	v_pk_fma_f32 v[4:5], v[4:5], v[6:7], v[8:9] op_sel_hi:[1,1,0]
	v_addc_co_u32_e32 v99, vcc, 0, v91, vcc
	v_cvt_pk_bf16_f32 v3, v4, v2
	global_store_dword v[12:13], v3, off offset:2048
	v_mov_b32_e32 v3, v4
	s_waitcnt lgkmcnt(0)
	global_store_dwordx2 v[10:11], v[2:3], off
	global_load_dwordx4 v[2:5], v[98:99], off offset:-4096
	v_mul_f32_e32 v6, 0xbfb8aa3b, v86
	s_mov_b32 s0, 0x23000
	v_exp_f32_e32 v84, v6
	v_add_co_u32_e32 v122, vcc, s0, v90
	s_mov_b64 s[0:1], 0x20000
	s_nop 0
	v_addc_co_u32_e32 v123, vcc, 0, v91, vcc
	global_load_dwordx4 v[6:9], v[122:123], off offset:-4096
	global_load_dwordx4 v[106:109], v[98:99], off offset:96
	v_lshl_add_u64 v[26:27], v[90:91], 0, s[0:1]
	s_mov_b32 s0, 0x22000
	v_add_f32_e32 v216, 1.0, v163
	v_add_f32_e32 v217, -1.0, v216
	v_log_f32_e32 v218, v216
	v_rcp_f32_e32 v219, v217
	v_cmp_eq_f32_e32 vcc, 0, v217
	v_mul_f32_e32 v218, v218, v163
	v_mul_f32_e32 v218, 0x3f317218, v218
	v_mul_f32_e32 v218, v218, v219
	v_cndmask_b32_e32 v100, v218, v163, vcc
	v_add_co_u32_e32 v30, vcc, s0, v90
	s_nop 1
	v_addc_co_u32_e32 v31, vcc, 0, v91, vcc
	global_load_dwordx4 v[10:13], v[26:27], off offset:32
	global_load_dwordx4 v[18:21], v[26:27], off offset:64
	global_load_dwordx4 v[14:17], v[30:31], off offset:32
	global_load_dwordx4 v[22:25], v[30:31], off offset:64
	global_load_dwordx4 v[26:29], v[26:27], off offset:96
	global_load_dwordx4 v[30:33], v[30:31], off offset:96
	global_load_dwordx4 v[90:93], v[98:99], off
	global_load_dwordx4 v[94:97], v[122:123], off
	s_waitcnt vmcnt(10)
	v_mfma_f32_32x32x16_bf16 v[34:49], v[70:73], v[2:5], 0
	global_load_dwordx4 v[102:105], v[98:99], off offset:32
	global_load_dwordx4 v[114:117], v[98:99], off offset:64
	global_load_dwordx4 v[110:113], v[122:123], off offset:32
	global_load_dwordx4 v[118:121], v[122:123], off offset:64
	global_load_dwordx4 v[164:167], v[122:123], off offset:96
	s_waitcnt vmcnt(14)
	v_mfma_f32_32x32x16_bf16 v[50:65], v[70:73], v[6:9], 0
	s_waitcnt vmcnt(12)
	v_mfma_f32_32x32x16_bf16 v[34:49], v[66:69], v[10:13], v[34:49]
	s_waitcnt vmcnt(10)
	v_mfma_f32_32x32x16_bf16 v[50:65], v[66:69], v[14:17], v[50:65]
	s_mov_b32 s0, 0x13f0f000
	v_mfma_f32_32x32x16_bf16 v[34:49], v[78:81], v[18:21], v[34:49]
	s_waitcnt vmcnt(9)
	v_mfma_f32_32x32x16_bf16 v[50:65], v[78:81], v[22:25], v[50:65]
	s_nop 0
	s_waitcnt vmcnt(8)
	v_mfma_f32_32x32x16_bf16 v[34:49], v[74:77], v[26:29], v[34:49]
	s_waitcnt vmcnt(7)
	v_mfma_f32_32x32x16_bf16 v[50:65], v[74:77], v[30:33], v[50:65]
	s_waitcnt vmcnt(6)
	v_mfma_f32_32x32x16_bf16 v[2:17], v[70:73], v[90:93], 0
	s_waitcnt vmcnt(5)
	v_mfma_f32_32x32x16_bf16 v[18:33], v[70:73], v[94:97], 0
	v_mul_f32_e32 v86, 0xbfb8aa3b, v159
	s_nop 0
	s_waitcnt vmcnt(4)
	v_mfma_f32_32x32x16_bf16 v[2:17], v[66:69], v[102:105], v[2:17]
	v_add_f32_e32 v216, 1.0, v84
	v_add_f32_e32 v217, -1.0, v216
	v_log_f32_e32 v218, v216
	v_rcp_f32_e32 v219, v217
	v_cmp_eq_f32_e32 vcc, 0, v217
	v_mul_f32_e32 v218, v218, v84
	v_mul_f32_e32 v218, 0x3f317218, v218
	v_mul_f32_e32 v218, v218, v219
	v_cndmask_b32_e32 v98, v218, v84, vcc
	v_mul_f32_e32 v102, 0xbfb8aa3b, v160
	v_add_co_u32_e32 v96, vcc, s0, v88
	s_mov_b32 s0, 0x13f0e000
	s_nop 0
	v_addc_co_u32_e32 v97, vcc, 0, v89, vcc
	s_waitcnt vmcnt(2)
	v_mfma_f32_32x32x16_bf16 v[18:33], v[66:69], v[110:113], v[18:33]
	v_add_co_u32_e32 v94, vcc, s0, v88
	s_mov_b32 s0, 0x13f0d000
	s_nop 0
	v_addc_co_u32_e32 v95, vcc, 0, v89, vcc
	v_add_co_u32_e32 v92, vcc, s0, v88
	v_mfma_f32_32x32x16_bf16 v[2:17], v[78:81], v[114:117], v[2:17]
	s_nop 0
	v_addc_co_u32_e32 v93, vcc, 0, v89, vcc
	s_mov_b32 s0, 0x13f0c000
	v_add_co_u32_e32 v90, vcc, s0, v88
	s_mov_b32 s0, 0x13f0b000
	s_nop 0
	v_addc_co_u32_e32 v91, vcc, 0, v89, vcc
	s_waitcnt vmcnt(1)
	v_mfma_f32_32x32x16_bf16 v[18:33], v[78:81], v[118:121], v[18:33]
	v_mul_f32_e32 v80, 0xbfb8aa3b, v161
	v_mul_f32_e32 v81, 0xbfb8aa3b, v162
	v_fmamk_f32 v34, v34, 0xbfb8aa3b, v80
	v_exp_f32_e32 v78, v34
	v_fmamk_f32 v34, v50, 0xbfb8aa3b, v81
	v_exp_f32_e32 v79, v34
	v_fmamk_f32 v36, v36, 0xbfb8aa3b, v80
	v_exp_f32_e32 v50, v36
	v_fmamk_f32 v36, v52, 0xbfb8aa3b, v81
	v_pk_add_f32 v[78:79], v[78:79], 1.0 op_sel_hi:[1,0]
	v_mfma_f32_32x32x16_bf16 v[2:17], v[74:77], v[106:109], v[2:17]
	v_mul_f32_e32 v34, v78, v79
	v_rcp_f32_e32 v84, v34
	v_fmamk_f32 v34, v35, 0xbfb8aa3b, v80
	v_fmamk_f32 v35, v51, 0xbfb8aa3b, v81
	v_exp_f32_e32 v34, v34
	v_exp_f32_e32 v35, v35
	v_exp_f32_e32 v51, v36
	v_mul_f32_e32 v79, v79, v84
	v_mul_f32_e32 v78, v78, v84
	v_pk_add_f32 v[34:35], v[34:35], 1.0 op_sel_hi:[1,0]
	v_pk_add_f32 v[50:51], v[50:51], 1.0 op_sel_hi:[1,0]
	v_mul_f32_e32 v36, v34, v35
	v_rcp_f32_e32 v36, v36
	v_mul_f32_e32 v52, v50, v51
	v_rcp_f32_e32 v52, v52
	s_waitcnt vmcnt(0)
; template <int DIR, int MODE> ...
;     ...
; #pragma unroll
;     for (int nt = 0; nt < 2; ++nt) {
;         const float nba = prm[DIR][nt][0], nbx = prm[DIR][nt][1], k8l = prm[DIR][nt][2];
; #pragma unroll
;         for (int i = 0; i < 16; ++i) {
;             const float d1 = 1.f + __builtin_amdgcn_exp2f(__builtin_fmaf(accR[nt][i], -1.4426950408889634f, nba));
;             const float d2 = 1.f + __builtin_amdgcn_exp2f(__builtin_fmaf(accI[nt][i], -1.4426950408889634f, nbx));
;             const float inv = __builtin_amdgcn_rcpf(d1 * d2), rr = inv * d2, ii = inv * d1;
;             const float av = __builtin_amdgcn_exp2f(k8l * rr);
;             accR[nt][i] = av; accI[nt][i] = __builtin_amdgcn_sqrtf(fmaxf(__builtin_fmaf(-av, av, 1.f), 0.f)) * ii; }
	v_mfma_f32_32x32x16_bf16 v[18:33], v[74:77], v[164:167], v[18:33]
	v_mul_f32_e32 v84, v35, v36
	v_mul_f32_e32 v99, v34, v36
	v_fmamk_f32 v34, v37, 0xbfb8aa3b, v80
	v_fmamk_f32 v35, v53, 0xbfb8aa3b, v81
	v_exp_f32_e32 v34, v34
	v_exp_f32_e32 v35, v35
	v_fmamk_f32 v36, v38, 0xbfb8aa3b, v80
	v_fmamk_f32 v37, v54, 0xbfb8aa3b, v81
	v_exp_f32_e32 v36, v36
	v_exp_f32_e32 v37, v37
	v_pk_add_f32 v[34:35], v[34:35], 1.0 op_sel_hi:[1,0]
	v_mul_f32_e32 v51, v51, v52
	v_mul_f32_e32 v38, v34, v35
	v_rcp_f32_e32 v38, v38
	v_pk_add_f32 v[36:37], v[36:37], 1.0 op_sel_hi:[1,0]
	v_mul_f32_e32 v50, v50, v52
	v_mul_f32_e32 v53, v36, v37
	v_rcp_f32_e32 v53, v53
	v_mul_f32_e32 v52, v35, v38
	v_mul_f32_e32 v54, v34, v38
	v_fmamk_f32 v34, v39, 0xbfb8aa3b, v80
	v_fmamk_f32 v35, v55, 0xbfb8aa3b, v81
	v_exp_f32_e32 v34, v34
	v_exp_f32_e32 v35, v35
	v_mul_f32_e32 v103, v37, v53
	v_fmamk_f32 v37, v40, 0xbfb8aa3b, v80
	v_exp_f32_e32 v38, v37
	v_fmamk_f32 v37, v56, 0xbfb8aa3b, v81
	v_pk_add_f32 v[34:35], v[34:35], 1.0 op_sel_hi:[1,0]
	v_exp_f32_e32 v39, v37
	v_mul_f32_e32 v37, v34, v35
	v_rcp_f32_e32 v37, v37
	v_mul_f32_e32 v53, v36, v53
	v_fmamk_f32 v36, v42, 0xbfb8aa3b, v80
	v_exp_f32_e32 v36, v36
	v_mul_f32_e32 v56, v35, v37
	v_mul_f32_e32 v104, v34, v37
	v_fmamk_f32 v34, v41, 0xbfb8aa3b, v80
	v_fmamk_f32 v35, v57, 0xbfb8aa3b, v81
	v_exp_f32_e32 v34, v34
	v_exp_f32_e32 v35, v35
	v_fmamk_f32 v37, v58, 0xbfb8aa3b, v81
	v_exp_f32_e32 v37, v37
	v_pk_add_f32 v[38:39], v[38:39], 1.0 op_sel_hi:[1,0]
	v_fmamk_f32 v44, v44, 0xbfb8aa3b, v80
	v_mul_f32_e32 v40, v38, v39
	v_rcp_f32_e32 v55, v40
	v_pk_add_f32 v[40:41], v[34:35], 1.0 op_sel_hi:[1,0]
	v_pk_add_f32 v[74:75], v[36:37], 1.0 op_sel_hi:[1,0]
	v_mul_f32_e32 v34, v40, v41
	v_rcp_f32_e32 v35, v34
	v_mul_f32_e32 v34, v74, v75
	v_rcp_f32_e32 v193, v34
	v_mov_b32_e32 v101, v75
	v_mul_f32_e32 v105, v39, v55
	v_mul_f32_e32 v57, v40, v35
	v_pk_mul_f32 v[76:77], v[100:101], v[192:193]
	v_mul_f32_e32 v42, v38, v55
	v_mul_f32_e32 v39, v76, v52
	v_exp_f32_e32 v40, v39
	v_mul_f32_e32 v38, v76, v51
	v_exp_f32_e32 v38, v38
	v_mul_f32_e32 v55, v41, v35
	v_fma_f32 v41, -v40, v40, 1.0 clamp
	v_mul_f32_e32 v51, v76, v56
	v_fma_f32 v39, -v38, v38, 1.0 clamp
	v_sqrt_f32_e32 v41, v41
	v_exp_f32_e32 v52, v51
	v_sqrt_f32_e32 v39, v39
	v_mul_f32_e32 v41, v54, v41
	v_fma_f32 v54, -v52, v52, 1.0
	v_max_f32_e32 v56, 0, v54
	v_mul_f32_e32 v54, v76, v105
	v_mul_f32_e32 v39, v50, v39
	v_mul_f32_e32 v50, v76, v103
	v_exp_f32_e32 v54, v54
	v_exp_f32_e32 v50, v50
	v_mul_f32_e32 v55, v76, v55
	v_sqrt_f32_e32 v58, v56
	v_exp_f32_e32 v56, v55
	v_fma_f32 v55, -v54, v54, 1.0 clamp
	v_fma_f32 v51, -v50, v50, 1.0 clamp
	v_sqrt_f32_e32 v55, v55
	v_sqrt_f32_e32 v51, v51
	v_fma_f32 v75, -v56, v56, 1.0 clamp
	v_mul_f32_e32 v55, v42, v55
	v_fmamk_f32 v42, v43, 0xbfb8aa3b, v80
	v_mul_f32_e32 v51, v53, v51
	v_mul_f32_e32 v53, v104, v58
	v_exp_f32_e32 v58, v42
	v_fmamk_f32 v42, v59, 0xbfb8aa3b, v81
	v_mul_f32_e32 v34, v76, v79
	v_sqrt_f32_e32 v75, v75
	v_exp_f32_e32 v59, v42
	v_exp_f32_e32 v34, v34
	v_mul_f32_e32 v42, v76, v77
	v_mul_f32_e32 v35, v76, v84
	v_mul_f32_e32 v57, v57, v75
	v_mul_f32_e32 v43, v74, v193
	v_exp_f32_e32 v42, v42
	v_pk_add_f32 v[74:75], v[58:59], 1.0 op_sel_hi:[1,0]
	v_exp_f32_e32 v36, v35
	v_fma_f32 v35, -v34, v34, 1.0 clamp
	v_mul_f32_e32 v58, v74, v75
	v_rcp_f32_e32 v59, v58
	v_sqrt_f32_e32 v35, v35
	v_fma_f32 v58, -v42, v42, 1.0 clamp
	v_sqrt_f32_e32 v77, v58
	v_mul_f32_e32 v58, v75, v59
	v_mul_f32_e32 v35, v78, v35
	v_mul_f32_e32 v58, v76, v58
	v_exp_f32_e32 v78, v44
	v_fmamk_f32 v44, v60, 0xbfb8aa3b, v81
	v_exp_f32_e32 v58, v58
	v_exp_f32_e32 v79, v44
	v_fmamk_f32 v45, v45, 0xbfb8aa3b, v80
	v_mul_f32_e32 v59, v74, v59
	v_fma_f32 v44, -v58, v58, 1.0 clamp
	v_pk_add_f32 v[78:79], v[78:79], 1.0 op_sel_hi:[1,0]
	v_mul_f32_e32 v60, v78, v79
	v_sqrt_f32_e32 v44, v44
	v_rcp_f32_e32 v75, v60
	v_exp_f32_e32 v60, v45
	v_fmamk_f32 v45, v61, 0xbfb8aa3b, v81
	v_exp_f32_e32 v61, v45
	v_mul_f32_e32 v59, v59, v44
	v_mul_f32_e32 v44, v79, v75
	v_mul_f32_e32 v44, v76, v44
	v_mul_f32_e32 v45, v78, v75
	v_exp_f32_e32 v44, v44
	v_pk_add_f32 v[74:75], v[60:61], 1.0 op_sel_hi:[1,0]
	v_fmamk_f32 v46, v46, 0xbfb8aa3b, v80
	v_mul_f32_e32 v60, v74, v75
	v_rcp_f32_e32 v61, v60
	v_fma_f32 v60, -v44, v44, 1.0 clamp
	v_mul_f32_e32 v43, v43, v77
	v_sqrt_f32_e32 v77, v60
	v_mul_f32_e32 v60, v75, v61
	v_exp_f32_e32 v78, v46
	v_fmamk_f32 v46, v62, 0xbfb8aa3b, v81
	v_mul_f32_e32 v60, v76, v60
	v_exp_f32_e32 v79, v46
	v_exp_f32_e32 v60, v60
	v_fmamk_f32 v47, v47, 0xbfb8aa3b, v80
	v_mul_f32_e32 v61, v74, v61
	v_pk_add_f32 v[78:79], v[78:79], 1.0 op_sel_hi:[1,0]
	v_fma_f32 v46, -v60, v60, 1.0 clamp
	v_mul_f32_e32 v62, v78, v79
	v_rcp_f32_e32 v75, v62
	v_exp_f32_e32 v62, v47
	v_fmamk_f32 v47, v63, 0xbfb8aa3b, v81
	v_sqrt_f32_e32 v46, v46
	v_exp_f32_e32 v63, v47
	v_mul_f32_e32 v47, v78, v75
	v_mul_f32_e32 v45, v45, v77
	v_mul_f32_e32 v61, v61, v46
	v_mul_f32_e32 v46, v79, v75
	v_pk_add_f32 v[62:63], v[62:63], 1.0 op_sel_hi:[1,0]
	v_mul_f32_e32 v46, v76, v46
	v_mul_f32_e32 v74, v62, v63
	v_exp_f32_e32 v46, v46
	v_rcp_f32_e32 v75, v74
	v_fmamk_f32 v48, v48, 0xbfb8aa3b, v80
	v_exp_f32_e32 v78, v48
	v_fma_f32 v74, -v46, v46, 1.0 clamp
	v_mul_f32_e32 v63, v63, v75
	v_mul_f32_e32 v63, v76, v63
	v_sqrt_f32_e32 v77, v74
	v_exp_f32_e32 v74, v63
	v_fmamk_f32 v48, v64, 0xbfb8aa3b, v81
	v_exp_f32_e32 v79, v48
	v_mul_f32_e32 v62, v62, v75
	v_fma_f32 v48, -v74, v74, 1.0 clamp
	v_sqrt_f32_e32 v48, v48
	v_pk_add_f32 v[78:79], v[78:79], 1.0 op_sel_hi:[1,0]
	v_fmac_f32_e32 v80, 0xbfb8aa3b, v49
	v_mul_f32_e32 v63, v78, v79
	v_fmac_f32_e32 v81, 0xbfb8aa3b, v65
	v_rcp_f32_e32 v63, v63
; template <int DIR, int MODE> ...
;     ...
; #pragma unroll
;     for (int nt = 0; nt < 2; ++nt) {
;         const float nba = prm[DIR][nt][0], nbx = prm[DIR][nt][1], k8l = prm[DIR][nt][2];
; #pragma unroll
;         for (int i = 0; i < 16; ++i) {
;             const float d1 = 1.f + __builtin_amdgcn_exp2f(__builtin_fmaf(accR[nt][i], -1.4426950408889634f, nba));
;             const float d2 = 1.f + __builtin_amdgcn_exp2f(__builtin_fmaf(accI[nt][i], -1.4426950408889634f, nbx));
;             const float inv = __builtin_amdgcn_rcpf(d1 * d2), rr = inv * d2, ii = inv * d1;
;             const float av = __builtin_amdgcn_exp2f(k8l * rr);
;             accR[nt][i] = av; accI[nt][i] = __builtin_amdgcn_sqrtf(fmaxf(__builtin_fmaf(-av, av, 1.f), 0.f)) * ii; }
	v_mul_f32_e32 v75, v62, v48
	v_exp_f32_e32 v48, v80
	v_exp_f32_e32 v49, v81
	v_mul_f32_e32 v62, v79, v63
	v_mul_f32_e32 v62, v76, v62
	v_exp_f32_e32 v62, v62
	v_pk_add_f32 v[48:49], v[48:49], 1.0 op_sel_hi:[1,0]
	v_mul_f32_e32 v63, v78, v63
	v_mul_f32_e32 v64, v48, v49
	v_rcp_f32_e32 v65, v64
	v_fma_f32 v64, -v62, v62, 1.0 clamp
	v_sqrt_f32_e32 v78, v64
	v_mul_f32_e32 v49, v49, v65
	v_mul_f32_e32 v49, v76, v49
	v_exp_f32_e32 v64, v49
	v_fmamk_f32 v2, v2, 0xbfb8aa3b, v86
	v_exp_f32_e32 v76, v2
	v_fmamk_f32 v2, v18, 0xbfb8aa3b, v102
	v_mul_f32_e32 v47, v47, v77
	v_exp_f32_e32 v77, v2
	v_fma_f32 v2, -v64, v64, 1.0 clamp
	v_sqrt_f32_e32 v2, v2
	v_pk_add_f32 v[76:77], v[76:77], 1.0 op_sel_hi:[1,0]
	v_fmamk_f32 v4, v4, 0xbfb8aa3b, v86
	v_mul_f32_e32 v18, v76, v77
	v_rcp_f32_e32 v49, v18
	v_mul_f32_e32 v18, v48, v65
	v_mul_f32_e32 v65, v18, v2
	v_fmamk_f32 v2, v3, 0xbfb8aa3b, v86
	v_fmamk_f32 v3, v19, 0xbfb8aa3b, v102
	v_exp_f32_e32 v2, v2
	v_exp_f32_e32 v3, v3
	v_exp_f32_e32 v18, v4
	v_fmamk_f32 v4, v20, 0xbfb8aa3b, v102
	v_exp_f32_e32 v19, v4
	v_pk_add_f32 v[2:3], v[2:3], 1.0 op_sel_hi:[1,0]
	v_mul_f32_e32 v48, v77, v49
	v_mul_f32_e32 v4, v2, v3
	v_rcp_f32_e32 v4, v4
	v_mul_f32_e32 v49, v76, v49
	v_pk_add_f32 v[18:19], v[18:19], 1.0 op_sel_hi:[1,0]
	v_mul_f32_e32 v63, v63, v78
	v_mul_f32_e32 v76, v3, v4
	v_mul_f32_e32 v77, v2, v4
	v_fmamk_f32 v2, v5, 0xbfb8aa3b, v86
	v_fmamk_f32 v3, v21, 0xbfb8aa3b, v102
	v_exp_f32_e32 v2, v2
	v_exp_f32_e32 v3, v3
	v_fmamk_f32 v4, v6, 0xbfb8aa3b, v86
	v_fmamk_f32 v5, v22, 0xbfb8aa3b, v102
	v_mul_f32_e32 v20, v18, v19
	v_exp_f32_e32 v4, v4
	v_exp_f32_e32 v5, v5
	v_pk_add_f32 v[2:3], v[2:3], 1.0 op_sel_hi:[1,0]
	v_rcp_f32_e32 v20, v20
	v_mul_f32_e32 v6, v2, v3
	v_rcp_f32_e32 v6, v6
	v_pk_add_f32 v[4:5], v[4:5], 1.0 op_sel_hi:[1,0]
	v_mul_f32_e32 v78, v19, v20
	v_mul_f32_e32 v19, v4, v5
	v_rcp_f32_e32 v19, v19
	v_mul_f32_e32 v80, v3, v6
	v_mul_f32_e32 v81, v2, v6
	v_fmamk_f32 v2, v7, 0xbfb8aa3b, v86
	v_fmamk_f32 v3, v23, 0xbfb8aa3b, v102
	v_exp_f32_e32 v2, v2
	v_exp_f32_e32 v3, v3
	v_mul_f32_e32 v84, v5, v19
	v_fmamk_f32 v5, v8, 0xbfb8aa3b, v86
	v_exp_f32_e32 v6, v5
	v_fmamk_f32 v5, v24, 0xbfb8aa3b, v102
	v_pk_add_f32 v[2:3], v[2:3], 1.0 op_sel_hi:[1,0]
	v_exp_f32_e32 v7, v5
	v_mul_f32_e32 v5, v2, v3
	v_rcp_f32_e32 v5, v5
	v_fma_f32 v37, -v36, v36, 1.0 clamp
	v_pk_add_f32 v[6:7], v[6:7], 1.0 op_sel_hi:[1,0]
	v_mul_f32_e32 v8, v6, v7
	v_mul_f32_e32 v101, v3, v5
	v_mul_f32_e32 v103, v2, v5
	v_fmamk_f32 v2, v10, 0xbfb8aa3b, v86
	v_fmamk_f32 v3, v26, 0xbfb8aa3b, v102
	v_rcp_f32_e32 v8, v8
	v_exp_f32_e32 v2, v2
	v_exp_f32_e32 v3, v3
	v_mul_f32_e32 v100, v4, v19
	v_mul_f32_e32 v104, v7, v8
	v_mul_f32_e32 v105, v6, v8
	v_fmamk_f32 v4, v9, 0xbfb8aa3b, v86
	v_pk_add_f32 v[8:9], v[2:3], 1.0 op_sel_hi:[1,0]
	v_sqrt_f32_e32 v37, v37
	v_mul_f32_e32 v2, v8, v9
	v_rcp_f32_e32 v193, v2
	v_fmamk_f32 v2, v25, 0xbfb8aa3b, v102
	v_exp_f32_e32 v4, v4
	v_exp_f32_e32 v5, v2
	v_mul_f32_e32 v37, v99, v37
	v_mov_b32_e32 v99, v9
	v_mul_f32_e32 v79, v18, v20
	v_pk_mul_f32 v[18:19], v[98:99], v[192:193]
	v_pk_add_f32 v[6:7], v[4:5], 1.0 op_sel_hi:[1,0]
	v_mul_f32_e32 v2, v18, v48
	v_exp_f32_e32 v2, v2
	v_mul_f32_e32 v3, v6, v7
	v_rcp_f32_e32 v3, v3
	v_mul_f32_e32 v9, v18, v19
	v_fma_f32 v4, -v2, v2, 1.0 clamp
	v_sqrt_f32_e32 v5, v4
	v_mul_f32_e32 v4, v18, v76
	v_mul_f32_e32 v76, v6, v3
	v_fmamk_f32 v6, v11, 0xbfb8aa3b, v86
	v_exp_f32_e32 v10, v6
	v_fmamk_f32 v6, v27, 0xbfb8aa3b, v102
	v_exp_f32_e32 v11, v6
	v_mul_f32_e32 v48, v7, v3
	v_exp_f32_e32 v20, v9
	v_mul_f32_e32 v8, v8, v193
	v_pk_add_f32 v[10:11], v[10:11], 1.0 op_sel_hi:[1,0]
	v_add_co_u32_e32 v72, vcc, s0, v88
	v_mul_f32_e32 v7, v10, v11
	v_rcp_f32_e32 v7, v7
	v_addc_co_u32_e32 v73, vcc, 0, v89, vcc
	s_mov_b32 s0, 0x13f0a000
	v_mul_f32_e32 v9, v11, v7
	v_mul_f32_e32 v9, v18, v9
	v_exp_f32_e32 v22, v9
	v_fma_f32 v9, -v20, v20, 1.0 clamp
	v_sqrt_f32_e32 v9, v9
	v_fma_f32 v11, -v22, v22, 1.0 clamp
	v_sqrt_f32_e32 v11, v11
	v_mul_f32_e32 v7, v10, v7
	v_mul_f32_e32 v21, v8, v9
	v_add_co_u32_e32 v70, vcc, s0, v88
	v_mul_f32_e32 v23, v7, v11
	v_fmamk_f32 v7, v12, 0xbfb8aa3b, v86
	v_exp_f32_e32 v8, v7
	v_fmamk_f32 v7, v28, 0xbfb8aa3b, v102
	v_exp_f32_e32 v9, v7
	v_fmamk_f32 v7, v13, 0xbfb8aa3b, v86
	v_exp_f32_e32 v10, v7
	v_fmamk_f32 v7, v29, 0xbfb8aa3b, v102
	v_exp_f32_e32 v11, v7
	v_pk_add_f32 v[8:9], v[8:9], 1.0 op_sel_hi:[1,0]
	v_addc_co_u32_e32 v71, vcc, 0, v89, vcc
	v_mul_f32_e32 v7, v8, v9
	v_rcp_f32_e32 v7, v7
	v_pk_add_f32 v[10:11], v[10:11], 1.0 op_sel_hi:[1,0]
	s_mov_b32 s0, 0x13f09000
	v_mul_f32_e32 v12, v10, v11
	v_rcp_f32_e32 v19, v12
	v_mul_f32_e32 v9, v9, v7
	v_mul_f32_e32 v9, v18, v9
	v_exp_f32_e32 v12, v9
	v_mul_f32_e32 v9, v11, v19
	v_mul_f32_e32 v9, v18, v9
	v_exp_f32_e32 v24, v9
	v_fma_f32 v9, -v12, v12, 1.0 clamp
	v_sqrt_f32_e32 v9, v9
	v_fma_f32 v11, -v24, v24, 1.0 clamp
	v_sqrt_f32_e32 v11, v11
	v_mul_f32_e32 v7, v8, v7
	v_mul_f32_e32 v13, v7, v9
	v_mul_f32_e32 v7, v10, v19
	v_mul_f32_e32 v25, v7, v11
	v_fmamk_f32 v7, v14, 0xbfb8aa3b, v86
	v_exp_f32_e32 v8, v7
	v_fmamk_f32 v7, v30, 0xbfb8aa3b, v102
	v_exp_f32_e32 v9, v7
	v_fmamk_f32 v7, v15, 0xbfb8aa3b, v86
	v_exp_f32_e32 v10, v7
	v_fmamk_f32 v7, v31, 0xbfb8aa3b, v102
	v_exp_f32_e32 v11, v7
	v_pk_add_f32 v[8:9], v[8:9], 1.0 op_sel_hi:[1,0]
	v_mul_f32_e32 v6, v18, v78
	v_mul_f32_e32 v7, v8, v9
	v_rcp_f32_e32 v7, v7
	v_pk_add_f32 v[10:11], v[10:11], 1.0 op_sel_hi:[1,0]
	v_add_co_u32_e32 v68, vcc, s0, v88
	v_mul_f32_e32 v14, v10, v11
	v_rcp_f32_e32 v19, v14
	v_mul_f32_e32 v9, v9, v7
	v_mul_f32_e32 v9, v18, v9
	v_exp_f32_e32 v14, v9
	v_mul_f32_e32 v9, v11, v19
	v_mul_f32_e32 v9, v18, v9
	v_exp_f32_e32 v26, v9
; __device__ __forceinline__ unsigned cvt_pk_bf16(float lo, float hi) { unsigned r; asm volatile("v_cvt_pk_bf16_f32 %0, %1, %2" : "=v"(r) : "v"(lo), "v"(hi)); return r; }
; #define LAS __attribute__((address_space(3)))
; #define LDS_WAVE_SYNC() asm volatile("s_waitcnt lgkmcnt(0)" ::: "memory")
; template <int DIR, int MODE> ...
;     ...
; #pragma unroll
;     for (int nt = 0; nt < 2; ++nt) {
;         const float nba = prm[DIR][nt][0], nbx = prm[DIR][nt][1], k8l = prm[DIR][nt][2];
; #pragma unroll
;         for (int i = 0; i < 16; ++i) {
;             const float d1 = 1.f + __builtin_amdgcn_exp2f(__builtin_fmaf(accR[nt][i], -1.4426950408889634f, nba));
;             const float d2 = 1.f + __builtin_amdgcn_exp2f(__builtin_fmaf(accI[nt][i], -1.4426950408889634f, nbx));
;             const float inv = __builtin_amdgcn_rcpf(d1 * d2), rr = inv * d2, ii = inv * d1;
;             const float av = __builtin_amdgcn_exp2f(k8l * rr);
;             accR[nt][i] = av; accI[nt][i] = __builtin_amdgcn_sqrtf(fmaxf(__builtin_fmaf(-av, av, 1.f), 0.f)) * ii; }
;     }
;     float hc = 0.f, ap = 1.f;
;     if (MODE == 1) hc = ((const float*)(a.ws + WS_CAR))[(size_t)((b * NCH + ch) * 2 + DIR) * LW + c];
; #pragma unroll
;     for (int hh = 0; hh < 2; ++hh) {
;         const int half = DIR == 0 ? hh : 1 - hh;
; #pragma unroll
;         for (int nt = 0; nt < 2; ++nt)
; #pragma unroll
;             for (int i = 0; i < 8; ++i) { const int tt = 8 * (i >> 2) + 4 * h + (i & 3);
;                 f32x2 v; v.x = accR[nt][8 * half + i]; v.y = accI[nt][8 * half + i];
;                 *(LAS f32x2*)(au + (tt * 64 + nt * 32 + r32) * 2) = v; }
;         LDS_WAVE_SYNC();
; #pragma unroll
;         for (int s = 0; s < 16; ++s) {
;             const int tt = DIR == 0 ? s : 15 - s, t = half * 16 + tt;
;             const f32x2 v = *(const LAS f32x2*)(au + (tt * 64 + lane) * 2);
;             hc = v.x * hc + v.y * xcr[t];
;             if (MODE == 0) { ap *= v.x;
;                 ((unsigned*)(a.ws + WS_HP))[((size_t)DIR * T + (size_t)b * SEQ + ch * 32 + t) * LW + c] = pg8::cvt_pk_bf16(hc, ap); }
	v_fma_f32 v9, -v14, v14, 1.0 clamp
	v_sqrt_f32_e32 v9, v9
	v_fma_f32 v11, -v26, v26, 1.0 clamp
	v_sqrt_f32_e32 v11, v11
	v_mul_f32_e32 v7, v8, v7
	v_mul_f32_e32 v15, v7, v9
	v_mul_f32_e32 v7, v10, v19
	v_mul_f32_e32 v27, v7, v11
	v_fmamk_f32 v7, v16, 0xbfb8aa3b, v86
	v_exp_f32_e32 v8, v7
	v_fmamk_f32 v7, v32, 0xbfb8aa3b, v102
	v_exp_f32_e32 v9, v7
	v_fmac_f32_e32 v86, 0xbfb8aa3b, v17
	v_fmac_f32_e32 v102, 0xbfb8aa3b, v33
	v_exp_f32_e32 v10, v86
	v_exp_f32_e32 v11, v102
	v_pk_add_f32 v[8:9], v[8:9], 1.0 op_sel_hi:[1,0]
	v_mov_b32_e32 v86, v1
	v_mul_f32_e32 v7, v8, v9
	v_rcp_f32_e32 v7, v7
	v_pk_add_f32 v[10:11], v[10:11], 1.0 op_sel_hi:[1,0]
	v_addc_co_u32_e32 v69, vcc, 0, v89, vcc
	v_mul_f32_e32 v16, v10, v11
	v_rcp_f32_e32 v19, v16
	v_mul_f32_e32 v9, v9, v7
	v_mul_f32_e32 v9, v18, v9
	v_exp_f32_e32 v16, v9
	v_mul_f32_e32 v9, v11, v19
	v_mul_f32_e32 v9, v18, v9
	v_exp_f32_e32 v28, v9
	v_fma_f32 v9, -v16, v16, 1.0 clamp
	v_sqrt_f32_e32 v9, v9
	v_fma_f32 v11, -v28, v28, 1.0 clamp
	v_sqrt_f32_e32 v11, v11
	v_mul_f32_e32 v7, v8, v7
	v_mul_f32_e32 v17, v7, v9
	v_mul_f32_e32 v7, v10, v19
	v_mul_f32_e32 v29, v7, v11
	ds_write2_b64 v124, v[42:43], v[20:21] offset0:64 offset1:96
	ds_write2_b64 v124, v[58:59], v[22:23] offset0:128 offset1:160
	ds_write2_b64 v124, v[44:45], v[12:13] offset0:192 offset1:224
	ds_write2_b64 v126, v[60:61], v[24:25] offset1:32
	ds_write2_b64 v127, v[46:47], v[14:15] offset0:64 offset1:96
	ds_write2_b64 v127, v[74:75], v[26:27] offset0:128 offset1:160
	ds_write2_b64 v127, v[62:63], v[16:17] offset0:192 offset1:224
	ds_write2_b64 v128, v[64:65], v[28:29] offset1:32
	s_waitcnt lgkmcnt(0)
	ds_read_b64 v[8:9], v125 offset:12288
	v_mul_f32_e32 v10, v18, v80
	v_exp_f32_e32 v10, v10
	v_mul_f32_e32 v19, v18, v101
	v_exp_f32_e32 v4, v4
	s_waitcnt lgkmcnt(0)
	v_mul_f32_e32 v12, v87, v9
	v_pk_fma_f32 v[12:13], v[86:87], v[8:9], v[12:13] op_sel_hi:[1,1,0]
	v_fma_f32 v17, -v10, v10, 1.0
	v_cvt_pk_bf16_f32 v11, v12, v8
	ds_read_b64 v[14:15], v125 offset:11776
	v_mov_b32_e32 v13, v158
	global_store_dword v[96:97], v11, off offset:2048
	v_exp_f32_e32 v6, v6
	s_mov_b32 s0, 0x13f08000
	s_waitcnt lgkmcnt(0)
	v_mul_f32_e32 v16, v158, v15
	v_pk_fma_f32 v[12:13], v[12:13], v[14:15], v[16:17] op_sel_hi:[1,1,0]
	v_pk_mul_f32 v[8:9], v[8:9], v[14:15]
	v_max_f32_e32 v13, 0, v17
	v_cvt_pk_bf16_f32 v11, v12, v8
	ds_read_b64 v[14:15], v125 offset:11264
	v_sqrt_f32_e32 v17, v13
	v_mov_b32_e32 v13, v157
	global_store_dword v[96:97], v11, off
	v_mul_f32_e32 v3, v49, v5
	s_waitcnt lgkmcnt(0)
	v_mul_f32_e32 v16, v157, v15
	v_pk_fma_f32 v[12:13], v[12:13], v[14:15], v[16:17] op_sel_hi:[1,1,0]
	v_pk_mul_f32 v[8:9], v[8:9], v[14:15]
	v_fma_f32 v5, -v4, v4, 1.0 clamp
	v_cvt_pk_bf16_f32 v13, v12, v8
	ds_read_b64 v[14:15], v125 offset:10752
	global_store_dword v[94:95], v13, off offset:2048
	v_mov_b32_e32 v13, v156
	v_fma_f32 v49, -v6, v6, 1.0
	v_mul_f32_e32 v11, v81, v17
	s_waitcnt lgkmcnt(0)
	v_mul_f32_e32 v16, v156, v15
	v_pk_fma_f32 v[12:13], v[12:13], v[14:15], v[16:17] op_sel_hi:[1,1,0]
	v_pk_mul_f32 v[8:9], v[8:9], v[14:15]
	v_mul_f32_e32 v16, v18, v84
	v_cvt_pk_bf16_f32 v13, v12, v8
	ds_read_b64 v[14:15], v125 offset:10240
	global_store_dword v[94:95], v13, off
	v_mov_b32_e32 v13, v155
	v_exp_f32_e32 v16, v16
	v_add_co_u32_e32 v66, vcc, s0, v88
	s_waitcnt lgkmcnt(0)
	v_mul_f32_e32 v20, v155, v15
	v_pk_fma_f32 v[12:13], v[12:13], v[14:15], v[20:21] op_sel_hi:[1,1,0]
	v_pk_mul_f32 v[8:9], v[8:9], v[14:15]
	v_fma_f32 v17, -v16, v16, 1.0 clamp
	v_cvt_pk_bf16_f32 v13, v12, v8
	ds_read_b64 v[14:15], v125 offset:9728
	global_store_dword v[92:93], v13, off offset:2048
	v_mov_b32_e32 v13, v154
	v_max_f32_e32 v7, 0, v49
	s_waitcnt lgkmcnt(0)
	v_mul_f32_e32 v20, v154, v15
	v_pk_fma_f32 v[12:13], v[12:13], v[14:15], v[20:21] op_sel_hi:[1,1,0]
	v_pk_mul_f32 v[8:9], v[8:9], v[14:15]
	v_exp_f32_e32 v20, v19
	v_cvt_pk_bf16_f32 v13, v12, v8
	ds_read_b64 v[14:15], v125 offset:9216
	global_store_dword v[92:93], v13, off
	v_mov_b32_e32 v13, v153
	v_fma_f32 v19, -v20, v20, 1.0 clamp
	s_waitcnt lgkmcnt(0)
	v_mul_f32_e32 v22, v153, v15
	v_pk_fma_f32 v[12:13], v[12:13], v[14:15], v[22:23] op_sel_hi:[1,1,0]
	v_pk_mul_f32 v[8:9], v[8:9], v[14:15]
	v_sqrt_f32_e32 v19, v19
	v_cvt_pk_bf16_f32 v13, v12, v8
	ds_read_b64 v[14:15], v125 offset:8704
	global_store_dword v[90:91], v13, off offset:2048
	v_mov_b32_e32 v13, v152
	v_mul_f32_e32 v21, v103, v19
	v_mul_f32_e32 v19, v18, v104
	s_waitcnt lgkmcnt(0)
	v_mul_f32_e32 v22, v152, v15
	v_pk_fma_f32 v[12:13], v[12:13], v[14:15], v[22:23] op_sel_hi:[1,1,0]
	v_pk_mul_f32 v[8:9], v[8:9], v[14:15]
	v_mul_f32_e32 v18, v18, v48
	v_cvt_pk_bf16_f32 v13, v12, v8
	ds_read_b64 v[14:15], v125 offset:8192
	global_store_dword v[90:91], v13, off
	v_mov_b32_e32 v13, v151
	v_exp_f32_e32 v18, v18
	s_waitcnt lgkmcnt(0)
	v_mul_f32_e32 v22, v151, v15
	v_pk_fma_f32 v[12:13], v[12:13], v[14:15], v[22:23] op_sel_hi:[1,1,0]
	v_pk_mul_f32 v[8:9], v[8:9], v[14:15]
	v_addc_co_u32_e32 v67, vcc, 0, v89, vcc
	v_cvt_pk_bf16_f32 v13, v12, v8
	ds_read_b64 v[14:15], v125 offset:7680
	global_store_dword v[72:73], v13, off offset:2048
	v_mov_b32_e32 v13, v150
	v_sqrt_f32_e32 v5, v5
	v_sqrt_f32_e32 v7, v7
	s_waitcnt lgkmcnt(0)
	v_mul_f32_e32 v22, v150, v15
	v_pk_fma_f32 v[12:13], v[12:13], v[14:15], v[22:23] op_sel_hi:[1,1,0]
	v_pk_mul_f32 v[8:9], v[8:9], v[14:15]
	v_fma_f32 v23, -v18, v18, 1.0 clamp
	v_cvt_pk_bf16_f32 v13, v12, v8
	ds_read_b64 v[14:15], v125 offset:7168
	global_store_dword v[72:73], v13, off
	v_mov_b32_e32 v13, v149
	v_exp_f32_e32 v22, v19
	s_waitcnt lgkmcnt(0)
; __device__ __forceinline__ unsigned cvt_pk_bf16(float lo, float hi) { unsigned r; asm volatile("v_cvt_pk_bf16_f32 %0, %1, %2" : "=v"(r) : "v"(lo), "v"(hi)); return r; }
; #define LAS __attribute__((address_space(3)))
; #define LDS_WAVE_SYNC() asm volatile("s_waitcnt lgkmcnt(0)" ::: "memory")
; template <int DIR, int MODE> ...
;     ...
; #pragma unroll
;     for (int hh = 0; hh < 2; ++hh) {
;         const int half = DIR == 0 ? hh : 1 - hh;
; #pragma unroll
;         for (int nt = 0; nt < 2; ++nt)
; #pragma unroll
;             for (int i = 0; i < 8; ++i) { const int tt = 8 * (i >> 2) + 4 * h + (i & 3);
;                 f32x2 v; v.x = accR[nt][8 * half + i]; v.y = accI[nt][8 * half + i];
;                 *(LAS f32x2*)(au + (tt * 64 + nt * 32 + r32) * 2) = v; }
;         LDS_WAVE_SYNC();
; #pragma unroll
;         for (int s = 0; s < 16; ++s) {
;             const int tt = DIR == 0 ? s : 15 - s, t = half * 16 + tt;
;             const f32x2 v = *(const LAS f32x2*)(au + (tt * 64 + lane) * 2);
;             hc = v.x * hc + v.y * xcr[t];
;             if (MODE == 0) { ap *= v.x;
;                 ((unsigned*)(a.ws + WS_HP))[((size_t)DIR * T + (size_t)b * SEQ + ch * 32 + t) * LW + c] = pg8::cvt_pk_bf16(hc, ap); }
;             if (MODE == 1) { if (DIR == 0) hf[t] = hc; else hf[t] = gl[t] * (hf[t] + hc); }
;         }
	v_mul_f32_e32 v24, v149, v15
	v_pk_fma_f32 v[12:13], v[12:13], v[14:15], v[24:25] op_sel_hi:[1,1,0]
	v_pk_mul_f32 v[8:9], v[8:9], v[14:15]
	v_fma_f32 v19, -v22, v22, 1.0 clamp
	v_cvt_pk_bf16_f32 v13, v12, v8
	ds_read_b64 v[14:15], v125 offset:6656
	global_store_dword v[70:71], v13, off offset:2048
	v_mov_b32_e32 v13, v148
	v_sqrt_f32_e32 v17, v17
	s_waitcnt lgkmcnt(0)
	v_mul_f32_e32 v24, v148, v15
	v_pk_fma_f32 v[12:13], v[12:13], v[14:15], v[24:25] op_sel_hi:[1,1,0]
	v_pk_mul_f32 v[8:9], v[8:9], v[14:15]
	v_sqrt_f32_e32 v19, v19
	v_cvt_pk_bf16_f32 v13, v12, v8
	ds_read_b64 v[14:15], v125 offset:6144
	global_store_dword v[70:71], v13, off
	v_mov_b32_e32 v13, v147
	v_mul_f32_e32 v5, v77, v5
	v_mul_f32_e32 v7, v79, v7
	s_waitcnt lgkmcnt(0)
	v_mul_f32_e32 v24, v147, v15
	v_pk_fma_f32 v[12:13], v[12:13], v[14:15], v[24:25] op_sel_hi:[1,1,0]
	v_pk_mul_f32 v[8:9], v[8:9], v[14:15]
	v_mul_f32_e32 v17, v100, v17
	v_cvt_pk_bf16_f32 v13, v12, v8
	ds_read_b64 v[14:15], v125 offset:5632
	global_store_dword v[68:69], v13, off offset:2048
	v_mov_b32_e32 v13, v146
	s_mov_b32 s0, 0x13f07000
	s_waitcnt lgkmcnt(0)
	v_mul_f32_e32 v24, v146, v15
	v_pk_fma_f32 v[12:13], v[12:13], v[14:15], v[24:25] op_sel_hi:[1,1,0]
	v_pk_mul_f32 v[8:9], v[8:9], v[14:15]
	v_sqrt_f32_e32 v25, v23
	v_cvt_pk_bf16_f32 v13, v12, v8
	ds_read_b64 v[14:15], v125 offset:5120
	global_store_dword v[68:69], v13, off
	v_mov_b32_e32 v13, v145
	v_mul_f32_e32 v23, v105, v19
	v_mul_f32_e32 v19, v76, v25
	s_waitcnt lgkmcnt(0)
	v_mul_f32_e32 v24, v145, v15
	v_pk_fma_f32 v[12:13], v[12:13], v[14:15], v[24:25] op_sel_hi:[1,1,0]
	v_pk_mul_f32 v[8:9], v[8:9], v[14:15]
	s_nop 0
	v_cvt_pk_bf16_f32 v13, v12, v8
	ds_read_b64 v[14:15], v125 offset:4608
	global_store_dword v[66:67], v13, off offset:2048
	v_mov_b32_e32 v13, v144
	s_waitcnt lgkmcnt(0)
	v_mul_f32_e32 v24, v144, v15
	v_pk_fma_f32 v[12:13], v[12:13], v[14:15], v[24:25] op_sel_hi:[1,1,0]
	v_pk_mul_f32 v[8:9], v[8:9], v[14:15]
	s_nop 0
	v_cvt_pk_bf16_f32 v13, v12, v8
	global_store_dword v[66:67], v13, off
	s_waitcnt lgkmcnt(0)
	ds_write2_b64 v124, v[34:35], v[2:3] offset0:64 offset1:96
	ds_write2_b64 v124, v[36:37], v[4:5] offset0:128 offset1:160
	ds_write2_b64 v124, v[38:39], v[6:7] offset0:192 offset1:224
	ds_write2_b64 v126, v[40:41], v[10:11] offset1:32
	ds_write2_b64 v127, v[50:51], v[16:17] offset0:64 offset1:96
	ds_write2_b64 v127, v[52:53], v[20:21] offset0:128 offset1:160
	ds_write2_b64 v127, v[54:55], v[22:23] offset0:192 offset1:224
	ds_write2_b64 v128, v[56:57], v[18:19] offset1:32
	s_waitcnt lgkmcnt(0)
	ds_read_b64 v[2:3], v125 offset:12288
	v_mov_b32_e32 v13, v143
	s_waitcnt lgkmcnt(0)
	v_mul_f32_e32 v4, v143, v3
	v_pk_fma_f32 v[4:5], v[12:13], v[2:3], v[4:5] op_sel_hi:[1,1,0]
	v_pk_mul_f32 v[2:3], v[8:9], v[2:3]
	v_add_co_u32_e32 v8, vcc, s0, v88
	v_cvt_pk_bf16_f32 v5, v4, v2
	ds_read_b64 v[6:7], v125 offset:11776
	s_nop 0
	v_addc_co_u32_e32 v9, vcc, 0, v89, vcc
	global_store_dword v[8:9], v5, off offset:2048
	v_mov_b32_e32 v5, v142
	s_waitcnt lgkmcnt(0)
	v_mul_f32_e32 v10, v142, v7
	v_pk_fma_f32 v[4:5], v[4:5], v[6:7], v[10:11] op_sel_hi:[1,1,0]
	v_pk_mul_f32 v[2:3], v[2:3], v[6:7]
	s_mov_b32 s0, 0x13f06000
	v_cvt_pk_bf16_f32 v5, v4, v2
	ds_read_b64 v[6:7], v125 offset:11264
	global_store_dword v[8:9], v5, off
	v_mov_b32_e32 v5, v141
	v_lshl_add_u64 v[12:13], s[40:41], 0, v[82:83]
	s_waitcnt lgkmcnt(0)
	v_mul_f32_e32 v8, v141, v7
	v_pk_fma_f32 v[4:5], v[4:5], v[6:7], v[8:9] op_sel_hi:[1,1,0]
	v_pk_mul_f32 v[2:3], v[2:3], v[6:7]
	v_add_co_u32_e32 v8, vcc, s0, v88
	v_cvt_pk_bf16_f32 v5, v4, v2
	ds_read_b64 v[6:7], v125 offset:10752
	s_nop 0
	v_addc_co_u32_e32 v9, vcc, 0, v89, vcc
	global_store_dword v[8:9], v5, off offset:2048
	v_mov_b32_e32 v5, v140
	s_waitcnt lgkmcnt(0)
	v_mul_f32_e32 v10, v140, v7
	v_pk_fma_f32 v[4:5], v[4:5], v[6:7], v[10:11] op_sel_hi:[1,1,0]
	v_pk_mul_f32 v[2:3], v[2:3], v[6:7]
	s_mov_b32 s0, 0x13f05000
	v_cvt_pk_bf16_f32 v5, v4, v2
	ds_read_b64 v[6:7], v125 offset:10240
	global_store_dword v[8:9], v5, off
	v_mov_b32_e32 v5, v139
	s_waitcnt lgkmcnt(0)
; __device__ __forceinline__ unsigned cvt_pk_bf16(float lo, float hi) { unsigned r; asm volatile("v_cvt_pk_bf16_f32 %0, %1, %2" : "=v"(r) : "v"(lo), "v"(hi)); return r; }
; #define LAS __attribute__((address_space(3)))
; #define LDS_WAVE_SYNC() asm volatile("s_waitcnt lgkmcnt(0)" ::: "memory")
; template <int DIR, int MODE> ...
;     ...
;         for (int s = 0; s < 16; ++s) {
;             const int tt = DIR == 0 ? s : 15 - s, t = half * 16 + tt;
;             const f32x2 v = *(const LAS f32x2*)(au + (tt * 64 + lane) * 2);
;             hc = v.x * hc + v.y * xcr[t];
;             if (MODE == 0) { ap *= v.x;
;                 ((unsigned*)(a.ws + WS_HP))[((size_t)DIR * T + (size_t)b * SEQ + ch * 32 + t) * LW + c] = pg8::cvt_pk_bf16(hc, ap); }
;             if (MODE == 1) { if (DIR == 0) hf[t] = hc; else hf[t] = gl[t] * (hf[t] + hc); }
;         }
;         LDS_WAVE_SYNC();
;     }
;     if (MODE == 0) { f32x2 v; v.x = ap; v.y = hc; ((f32x2*)(a.ws + WS_TOT))[(size_t)((b * NCH + ch) * 2 + DIR) * LW + c] = v; }
	v_mul_f32_e32 v8, v139, v7
	v_pk_fma_f32 v[4:5], v[4:5], v[6:7], v[8:9] op_sel_hi:[1,1,0]
	v_pk_mul_f32 v[2:3], v[2:3], v[6:7]
	v_add_co_u32_e32 v8, vcc, s0, v88
	v_cvt_pk_bf16_f32 v5, v4, v2
	ds_read_b64 v[6:7], v125 offset:9728
	s_nop 0
	v_addc_co_u32_e32 v9, vcc, 0, v89, vcc
	global_store_dword v[8:9], v5, off offset:2048
	v_mov_b32_e32 v5, v138
	s_waitcnt lgkmcnt(0)
	v_mul_f32_e32 v10, v138, v7
	v_pk_fma_f32 v[4:5], v[4:5], v[6:7], v[10:11] op_sel_hi:[1,1,0]
	v_pk_mul_f32 v[2:3], v[2:3], v[6:7]
	s_mov_b32 s0, 0x13f04000
	v_cvt_pk_bf16_f32 v5, v4, v2
	ds_read_b64 v[6:7], v125 offset:9216
	global_store_dword v[8:9], v5, off
	v_mov_b32_e32 v5, v137
	s_waitcnt lgkmcnt(0)
	v_mul_f32_e32 v8, v137, v7
	v_pk_fma_f32 v[4:5], v[4:5], v[6:7], v[8:9] op_sel_hi:[1,1,0]
	v_pk_mul_f32 v[2:3], v[2:3], v[6:7]
	v_add_co_u32_e32 v8, vcc, s0, v88
	v_cvt_pk_bf16_f32 v5, v4, v2
	ds_read_b64 v[6:7], v125 offset:8704
	s_nop 0
	v_addc_co_u32_e32 v9, vcc, 0, v89, vcc
	global_store_dword v[8:9], v5, off offset:2048
	v_mov_b32_e32 v5, v136
	s_waitcnt lgkmcnt(0)
	v_mul_f32_e32 v10, v136, v7
	v_pk_fma_f32 v[4:5], v[4:5], v[6:7], v[10:11] op_sel_hi:[1,1,0]
	v_pk_mul_f32 v[2:3], v[2:3], v[6:7]
	s_mov_b32 s0, 0x13f03000
	v_cvt_pk_bf16_f32 v5, v4, v2
	ds_read_b64 v[6:7], v125 offset:8192
	global_store_dword v[8:9], v5, off
	v_mov_b32_e32 v5, v135
	s_waitcnt lgkmcnt(0)
	v_mul_f32_e32 v8, v135, v7
	v_pk_fma_f32 v[4:5], v[4:5], v[6:7], v[8:9] op_sel_hi:[1,1,0]
	v_pk_mul_f32 v[2:3], v[2:3], v[6:7]
	v_add_co_u32_e32 v8, vcc, s0, v88
	v_cvt_pk_bf16_f32 v5, v4, v2
	ds_read_b64 v[6:7], v125 offset:7680
	s_nop 0
	v_addc_co_u32_e32 v9, vcc, 0, v89, vcc
	global_store_dword v[8:9], v5, off offset:2048
	v_mov_b32_e32 v5, v134
	s_waitcnt lgkmcnt(0)
	v_mul_f32_e32 v10, v134, v7
	v_pk_fma_f32 v[4:5], v[4:5], v[6:7], v[10:11] op_sel_hi:[1,1,0]
	v_pk_mul_f32 v[2:3], v[2:3], v[6:7]
	s_mov_b32 s0, 0x13f02000
	v_cvt_pk_bf16_f32 v5, v4, v2
	ds_read_b64 v[6:7], v125 offset:7168
	global_store_dword v[8:9], v5, off
	v_mov_b32_e32 v5, v133
	s_waitcnt lgkmcnt(0)
	v_mul_f32_e32 v8, v133, v7
	v_pk_fma_f32 v[4:5], v[4:5], v[6:7], v[8:9] op_sel_hi:[1,1,0]
	v_pk_mul_f32 v[2:3], v[2:3], v[6:7]
	v_add_co_u32_e32 v8, vcc, s0, v88
	v_cvt_pk_bf16_f32 v5, v4, v2
	ds_read_b64 v[6:7], v125 offset:6656
	s_nop 0
	v_addc_co_u32_e32 v9, vcc, 0, v89, vcc
	global_store_dword v[8:9], v5, off offset:2048
	v_mov_b32_e32 v5, v132
	s_waitcnt lgkmcnt(0)
	v_mul_f32_e32 v10, v132, v7
	v_pk_fma_f32 v[4:5], v[4:5], v[6:7], v[10:11] op_sel_hi:[1,1,0]
	v_pk_mul_f32 v[2:3], v[2:3], v[6:7]
	s_mov_b32 s0, 0x13f01000
	v_cvt_pk_bf16_f32 v5, v4, v2
	ds_read_b64 v[6:7], v125 offset:6144
	global_store_dword v[8:9], v5, off
	v_mov_b32_e32 v5, v131
	v_add_co_u32_e32 v10, vcc, s0, v88
	s_waitcnt lgkmcnt(0)
	v_mul_f32_e32 v8, v131, v7
	v_pk_fma_f32 v[4:5], v[4:5], v[6:7], v[8:9] op_sel_hi:[1,1,0]
	v_pk_mul_f32 v[2:3], v[2:3], v[6:7]
	v_addc_co_u32_e32 v11, vcc, 0, v89, vcc
	v_cvt_pk_bf16_f32 v5, v4, v2
	ds_read_b64 v[6:7], v125 offset:5632
	global_store_dword v[10:11], v5, off offset:2048
	v_mov_b32_e32 v5, v130
	s_mov_b32 s0, 0x13f00000
	v_add_co_u32_e32 v8, vcc, s0, v88
	s_waitcnt lgkmcnt(0)
	v_mul_f32_e32 v14, v130, v7
	v_pk_fma_f32 v[4:5], v[4:5], v[6:7], v[14:15] op_sel_hi:[1,1,0]
	v_pk_mul_f32 v[2:3], v[2:3], v[6:7]
	v_addc_co_u32_e32 v9, vcc, 0, v89, vcc
	v_cvt_pk_bf16_f32 v5, v4, v2
	ds_read_b64 v[6:7], v125 offset:5120
	global_store_dword v[10:11], v5, off
	v_mov_b32_e32 v5, v0
	v_add_co_u32_e32 v12, vcc, 0x11901000, v12
	s_waitcnt lgkmcnt(0)
	v_mul_f32_e32 v0, v0, v7
	v_pk_fma_f32 v[4:5], v[4:5], v[6:7], v[0:1] op_sel_hi:[1,1,0]
	v_pk_mul_f32 v[2:3], v[2:3], v[6:7]
	v_mov_b32_e32 v5, v85
	v_cvt_pk_bf16_f32 v0, v4, v2
	ds_read_b64 v[6:7], v125 offset:4608
	global_store_dword v[8:9], v0, off offset:2048
	v_addc_co_u32_e32 v13, vcc, 0, v13, vcc
	s_mov_b64 s[0:1], 0
	s_waitcnt lgkmcnt(0)
	v_mul_f32_e32 v0, v85, v7
	v_pk_fma_f32 v[4:5], v[4:5], v[6:7], v[0:1] op_sel_hi:[1,1,0]
	v_pk_mul_f32 v[2:3], v[2:3], v[6:7]
	s_nop 0
	v_cvt_pk_bf16_f32 v0, v4, v2
	global_store_dword v[8:9], v0, off
	s_waitcnt lgkmcnt(0)
	v_mov_b32_e32 v3, v4
	global_store_dwordx2 v[12:13], v[2:3], off
